# attention softmax: scale-subtract fma pairs packed into v_pk_fma_f32 (36 pairs)
# baseline (speedup 1.0000x reference)
.LBB0_925:
	ds_read_b128 v[12:15], v9
	ds_read_b128 v[22:25], v9 offset:64
	ds_read_b128 v[26:29], v9 offset:2304
	ds_read_b128 v[50:53], v9 offset:2368
	ds_read_b128 v[54:57], v9 offset:4608
	ds_read_b128 v[58:61], v9 offset:4672
	ds_read_b128 v[62:65], v9 offset:6912
	ds_read_b128 v[66:69], v9 offset:6976
	s_waitcnt vmcnt(1) lgkmcnt(7)
	v_mfma_f32_16x16x32_bf16 v[12:15], v[12:15], v[4:7], 0
	v_add_u32_e32 v10, s8, v153
	v_cmp_lt_i32_e32 vcc, v10, v20
	s_add_i32 s8, s8, 64
	s_waitcnt vmcnt(0) lgkmcnt(6)
	v_mfma_f32_16x16x32_bf16 v[12:15], v[22:25], v[0:3], v[12:15]
	v_add_u32_e32 v9, 0x2400, v9
	s_cmp_eq_u32 s76, s8
	s_waitcnt lgkmcnt(5)
	v_mfma_f32_16x16x32_bf16 v[22:25], v[26:29], v[4:7], 0
	s_waitcnt lgkmcnt(4)
	s_nop 0
	v_mfma_f32_16x16x32_bf16 v[22:25], v[50:53], v[0:3], v[22:25]
	s_nop 1
	v_cndmask_b32_e32 v16, v246, v12, vcc
	v_add_u32_e32 v12, 1, v10
	v_cmp_lt_i32_e32 vcc, v12, v20
	s_waitcnt lgkmcnt(3)
	v_mfma_f32_16x16x32_bf16 v[26:29], v[54:57], v[4:7], 0
	v_cndmask_b32_e32 v21, v246, v13, vcc
	v_add_u32_e32 v13, 2, v10
	v_cmp_lt_i32_e32 vcc, v13, v20
	v_add_u32_e32 v13, 3, v10
	s_waitcnt lgkmcnt(2)
	v_mfma_f32_16x16x32_bf16 v[26:29], v[58:61], v[0:3], v[26:29]
	v_cndmask_b32_e32 v14, v246, v14, vcc
	v_cmp_lt_i32_e32 vcc, v13, v20
	v_add_u32_e32 v13, 16, v10
	s_waitcnt lgkmcnt(1)
	v_mfma_f32_16x16x32_bf16 v[50:53], v[62:65], v[4:7], 0
	v_cndmask_b32_e32 v15, v246, v15, vcc
	v_cmp_lt_i32_e32 vcc, v13, v20
	v_add_u32_e32 v13, 17, v10
	s_waitcnt lgkmcnt(0)
	v_mfma_f32_16x16x32_bf16 v[50:53], v[66:69], v[0:3], v[50:53]
	v_cndmask_b32_e32 v22, v246, v22, vcc
	v_cmp_lt_i32_e32 vcc, v13, v20
	v_add_u32_e32 v13, 18, v10
	v_max3_f32 v12, v16, s96, v21
	v_cndmask_b32_e32 v23, v246, v23, vcc
	v_cmp_lt_i32_e32 vcc, v13, v20
	v_add_u32_e32 v13, 19, v10
	v_max3_f32 v12, v12, v14, v15
	v_cndmask_b32_e32 v24, v246, v24, vcc
	v_cmp_lt_i32_e32 vcc, v13, v20
	v_add_u32_e32 v13, 32, v10
	v_max3_f32 v12, v12, v22, v23
	v_cndmask_b32_e32 v25, v246, v25, vcc
	v_cmp_lt_i32_e32 vcc, v13, v20
	v_add_u32_e32 v13, 33, v10
	v_max3_f32 v12, v12, v24, v25
	v_cndmask_b32_e32 v26, v246, v26, vcc
	v_cmp_lt_i32_e32 vcc, v13, v20
	v_add_u32_e32 v13, 34, v10
	s_nop 0
	v_cndmask_b32_e32 v27, v246, v27, vcc
	v_cmp_lt_i32_e32 vcc, v13, v20
	v_add_u32_e32 v13, 35, v10
	v_max3_f32 v12, v12, v26, v27
	v_cndmask_b32_e32 v28, v246, v28, vcc
	v_cmp_lt_i32_e32 vcc, v13, v20
	v_add_u32_e32 v13, 48, v10
	s_nop 0
	v_cndmask_b32_e32 v29, v246, v29, vcc
	v_cmp_lt_i32_e32 vcc, v13, v20
	v_add_u32_e32 v13, 49, v10
	v_max3_f32 v12, v12, v28, v29
	v_cndmask_b32_e32 v33, v246, v50, vcc
	v_cmp_lt_i32_e32 vcc, v13, v20
	s_nop 1
	v_cndmask_b32_e32 v35, v246, v51, vcc
	v_max3_f32 v13, v12, v33, v35
	v_add_u32_e32 v12, 50, v10
	v_cmp_lt_i32_e32 vcc, v12, v20
	v_add_u32_e32 v10, 51, v10
	s_nop 0
	v_cndmask_b32_e32 v37, v246, v52, vcc
	v_cmp_lt_i32_e32 vcc, v10, v20
	s_nop 1
	v_cndmask_b32_e32 v12, v246, v53, vcc
	v_max3_f32 v10, v13, v37, v12
	v_mov_b32_e32 v13, v10
	s_nop 1
	v_permlane16_swap_b32_e32 v10, v13
	v_max_f32_e32 v13, v13, v13
	v_max_f32_e32 v10, v10, v10
	v_max_f32_e32 v10, v10, v13
	v_mov_b32_e32 v13, v10
	s_nop 1
	v_permlane32_swap_b32_e32 v10, v13
	v_max3_f32 v10, v11, v10, v13
	v_max_f32_e32 v13, 0xe0ad78ec, v10
	v_pk_mul_f32 v[18:19], v[12:13], s[70:71] op_sel_hi:[1,0]
	v_sub_f32_e32 v11, v11, v10
	v_fma_f32 v12, v16, s70, -v19
	v_exp_f32_e32 v12, v12
	v_fma_f32 v13, v21, s70, -v19
	v_exp_f32_e32 v13, v13
	v_mul_f32_e32 v11, 0x3e38aa3b, v11
	v_add_f32_e32 v12, 0, v12
	v_exp_f32_e32 v11, v11
	v_add_f32_e32 v12, v13, v12
	v_fma_f32 v13, v14, s70, -v19
	v_exp_f32_e32 v13, v13
	s_nop 0
	v_add_f32_e32 v12, v13, v12
	v_fma_f32 v13, v15, s70, -v19
	v_exp_f32_e32 v13, v13
	s_nop 0
	v_add_f32_e32 v12, v13, v12
	v_fma_f32 v13, v22, s70, -v19
	v_exp_f32_e32 v13, v13
	s_nop 0
	v_add_f32_e32 v12, v13, v12
	v_fma_f32 v13, v23, s70, -v19
	v_exp_f32_e32 v13, v13
	s_nop 0
	v_add_f32_e32 v12, v13, v12
	v_fma_f32 v13, v24, s70, -v19
	v_exp_f32_e32 v13, v13
	s_nop 0
	v_add_f32_e32 v12, v13, v12
	v_fma_f32 v13, v25, s70, -v19
	v_exp_f32_e32 v13, v13
	s_nop 0
	v_add_f32_e32 v12, v13, v12
	v_fma_f32 v13, v26, s70, -v19
	v_exp_f32_e32 v13, v13
	s_nop 0
	v_add_f32_e32 v12, v13, v12
	v_fma_f32 v13, v27, s70, -v19
	v_exp_f32_e32 v13, v13
	s_nop 0
	v_add_f32_e32 v12, v13, v12
	v_fma_f32 v13, v28, s70, -v19
	v_exp_f32_e32 v13, v13
	s_nop 0
	v_add_f32_e32 v12, v13, v12
	v_fma_f32 v13, v29, s70, -v19
	v_exp_f32_e32 v13, v13
	s_nop 0
	v_add_f32_e32 v12, v13, v12
	v_fma_f32 v13, v33, s70, -v19
	v_exp_f32_e32 v13, v13
	s_nop 0
	v_add_f32_e32 v12, v13, v12
	v_fma_f32 v13, v35, s70, -v19
	v_exp_f32_e32 v13, v13
	s_nop 0
	v_add_f32_e32 v12, v13, v12
	v_fma_f32 v13, v37, s70, -v19
	v_exp_f32_e32 v13, v13
	s_nop 0
	v_add_f32_e32 v12, v13, v12
	v_sub_f32_e32 v13, v18, v19
	v_exp_f32_e32 v13, v13
	s_nop 0
	v_add_f32_e32 v12, v13, v12
	v_mov_b32_e32 v13, v8
	v_mov_b32_e32 v8, v12
	v_fmac_f32_e32 v8, v13, v11
	v_mov_b32_e32 v11, v10
	s_cbranch_scc0 .LBB0_925
	v_mov_b32_e32 v9, v8
	s_nop 1
	v_permlane16_swap_b32_e32 v8, v9
	v_add_f32_e32 v12, v8, v9
	ds_read_b128 v[8:11], v38
	v_mov_b32_e32 v13, v12
	s_nop 1
	v_permlane32_swap_b32_e32 v12, v13
	v_add_f32_e32 v12, v12, v13
	v_max_f32_e32 v16, 0xda24260, v12
	ds_read_b128 v[12:15], v38 offset:64
	v_div_scale_f32 v18, s[8:9], v16, v16, 1.0
	v_rcp_f32_e32 v21, v18
	ds_read_b128 v[22:25], v38 offset:2304
	s_waitcnt lgkmcnt(2)
	v_mfma_f32_16x16x32_bf16 v[8:11], v[8:11], v[4:7], 0
	ds_read_b128 v[50:53], v38 offset:4672
	v_fma_f32 v26, -v18, v21, 1.0
	v_fmac_f32_e32 v21, v26, v21
	ds_read_b128 v[26:29], v38 offset:2368
	s_waitcnt lgkmcnt(3)
	v_mfma_f32_16x16x32_bf16 v[8:11], v[12:15], v[0:3], v[8:11]
	ds_read_b128 v[12:15], v38 offset:4608
	v_div_scale_f32 v33, vcc, 1.0, v16, 1.0
	s_waitcnt lgkmcnt(3)
	v_mfma_f32_16x16x32_bf16 v[22:25], v[22:25], v[4:7], 0
	v_mul_f32_e32 v35, v33, v21
	v_fma_f32 v37, -v18, v35, v33
	s_nop 1
	v_pk_fma_f32 v[8:9], v[8:9], s[70:71], v[18:19] op_sel:[0,0,1] op_sel_hi:[1,0,1] neg_lo:[0,0,1] neg_hi:[0,0,1]
	s_waitcnt lgkmcnt(1)
	v_mfma_f32_16x16x32_bf16 v[22:25], v[26:29], v[0:3], v[22:25]
	v_fmac_f32_e32 v35, v37, v21
	v_exp_f32_e32 v8, v8
	s_waitcnt lgkmcnt(0)
	v_mfma_f32_16x16x32_bf16 v[12:15], v[12:15], v[4:7], 0
	v_fma_f32 v18, -v18, v35, v33
	v_exp_f32_e32 v9, v9
	v_pk_fma_f32 v[10:11], v[10:11], s[70:71], v[18:19] op_sel:[0,0,1] op_sel_hi:[1,0,1] neg_lo:[0,0,1] neg_hi:[0,0,1]
	v_div_fmas_f32 v18, v18, v21, v35
	v_exp_f32_e32 v10, v10
	v_div_fixup_f32 v16, v18, v16, 1.0
	v_mfma_f32_16x16x32_bf16 v[12:15], v[50:53], v[0:3], v[12:15]
	v_exp_f32_e32 v11, v11
	v_fma_f32 v21, v22, s70, -v19
	v_mul_f32_e32 v8, v16, v8
	v_cmp_lt_i32_e32 vcc, v153, v20
	v_or_b32_e32 v154, 1, v153
	v_exp_f32_e32 v21, v21
	v_fma_f32 v22, v23, s70, -v19
	v_cndmask_b32_e32 v8, 0, v8, vcc
	v_mul_f32_e32 v9, v16, v9
	v_cmp_lt_i32_e32 vcc, v154, v20
	v_or_b32_e32 v155, 2, v153
	v_exp_f32_e32 v22, v22
	v_fma_f32 v23, v24, s70, -v19
	ds_read_b128 v[26:29], v38 offset:6912
	ds_read_b128 v[54:57], v38 offset:6976
	v_cndmask_b32_e32 v9, 0, v9, vcc
	v_mul_f32_e32 v10, v16, v10
	v_cmp_lt_i32_e32 vcc, v155, v20
	v_or_b32_e32 v156, 3, v153
	v_exp_f32_e32 v23, v23
	v_fma_f32 v24, v25, s70, -v19
	v_cndmask_b32_e32 v10, 0, v10, vcc
	v_mul_f32_e32 v11, v16, v11
	v_cmp_lt_i32_e32 vcc, v156, v20
	v_or_b32_e32 v158, 16, v153
	v_exp_f32_e32 v24, v24
	v_pk_fma_f32 v[12:13], v[12:13], s[70:71], v[18:19] op_sel:[0,0,1] op_sel_hi:[1,0,1] neg_lo:[0,0,1] neg_hi:[0,0,1]
	v_cndmask_b32_e32 v11, 0, v11, vcc
	v_mul_f32_e32 v21, v16, v21
	v_cmp_lt_i32_e32 vcc, v158, v20
	v_or_b32_e32 v159, 17, v153
	v_exp_f32_e32 v12, v12
	v_cndmask_b32_e32 v21, 0, v21, vcc
	v_mul_f32_e32 v22, v16, v22
	v_cmp_lt_i32_e32 vcc, v159, v20
	v_or_b32_e32 v160, 18, v153
	v_exp_f32_e32 v13, v13
	v_cndmask_b32_e32 v22, 0, v22, vcc
	v_mul_f32_e32 v23, v16, v23
	v_cmp_lt_i32_e32 vcc, v160, v20
	v_or_b32_e32 v161, 19, v153
	v_mul_f32_e32 v24, v16, v24
	v_cndmask_b32_e32 v23, 0, v23, vcc
	v_cmp_lt_i32_e32 vcc, v161, v20
	v_or_b32_e32 v162, 32, v153
	v_mul_f32_e32 v12, v16, v12
	v_cndmask_b32_e32 v24, 0, v24, vcc
	v_cmp_lt_i32_e32 vcc, v162, v20
	s_waitcnt lgkmcnt(1)
	v_mfma_f32_16x16x32_bf16 v[26:29], v[26:29], v[4:7], 0
	v_or_b32_e32 v163, 33, v153
	v_cndmask_b32_e32 v33, 0, v12, vcc
	v_mul_f32_e32 v12, v16, v13
	v_fma_f32 v13, v14, s70, -v19
	v_exp_f32_e32 v13, v13
	v_cmp_lt_i32_e32 vcc, v163, v20
	s_waitcnt lgkmcnt(0)
	v_mfma_f32_16x16x32_bf16 v[26:29], v[54:57], v[0:3], v[26:29]
	v_or_b32_e32 v164, 34, v153
	v_cndmask_b32_e32 v37, 0, v12, vcc
	v_mul_f32_e32 v12, v16, v13
	v_fma_f32 v13, v15, s70, -v19
	v_exp_f32_e32 v13, v13
	v_cmp_lt_i32_e32 vcc, v164, v20
	v_or_b32_e32 v165, 35, v153
	v_or_b32_e32 v166, 48, v153
	v_cndmask_b32_e32 v41, 0, v12, vcc
	v_mul_f32_e32 v12, v16, v13
	v_fma_f32 v13, v26, s70, -v19
	v_exp_f32_e32 v13, v13
	v_cmp_lt_i32_e32 vcc, v165, v20
	v_or_b32_e32 v167, 49, v153
	v_or_b32_e32 v168, 50, v153
	v_cndmask_b32_e32 v51, 0, v12, vcc
	v_mul_f32_e32 v12, v16, v13
	v_fma_f32 v13, v27, s70, -v19
	v_exp_f32_e32 v13, v13
	v_cmp_lt_i32_e32 vcc, v166, v20
	v_or_b32_e32 v169, 51, v153
	v_lshlrev_b32_e32 v48, 3, v44
	v_cndmask_b32_e32 v63, 0, v12, vcc
	v_mul_f32_e32 v12, v16, v13
	v_fma_f32 v13, v28, s70, -v19
	v_exp_f32_e32 v13, v13
	v_cmp_lt_i32_e32 vcc, v167, v20
	v_and_b32_e32 v18, 24, v48
	v_or_b32_e32 v47, v153, v42
	v_cndmask_b32_e32 v68, 0, v12, vcc
	v_mul_f32_e32 v12, v16, v13
	v_fma_f32 v13, v29, s70, -v19
	v_exp_f32_e32 v13, v13
	v_cmp_lt_i32_e32 vcc, v168, v20
	v_add_u32_e32 v39, s97, v18
	s_movk_i32 s8, 0x90
	v_cndmask_b32_e32 v69, 0, v12, vcc
	v_mul_f32_e32 v12, v16, v13
	v_cmp_lt_i32_e32 vcc, v169, v20
	v_cvt_pk_bf16_f32 v26, v8, v9
	v_cvt_pk_bf16_f32 v27, v10, v11
	v_cvt_pk_bf16_f32 v28, v21, v22
	v_cvt_pk_bf16_f32 v29, v23, v24
	v_cvt_pk_bf16_f32 v72, v33, v37
	s_nop 1
	v_cndmask_b32_e32 v71, 0, v12, vcc
	v_add_f32_e32 v12, v8, v9
	v_cvt_pk_bf16_f32 v73, v41, v51
	v_cvt_pk_bf16_f32 v74, v63, v68
	v_cvt_pk_bf16_f32 v75, v69, v71
	v_mad_u32_u24 v40, v47, s8, v39
	s_nop 0
	v_add_f32_dpp v56, v12, v12 quad_perm:[1,0,3,2] row_mask:0xf bank_mask:0xf bound_ctrl:1
	v_add_f32_e32 v12, v10, v11
	v_add_f32_e32 v18, v33, v37
	v_mov_b32_e32 v58, 0
	v_add_f32_dpp v52, v12, v12 quad_perm:[1,0,3,2] row_mask:0xf bank_mask:0xf bound_ctrl:1
	v_add_f32_e32 v12, v21, v22
	v_add_f32_dpp v60, v18, v18 quad_perm:[1,0,3,2] row_mask:0xf bank_mask:0xf bound_ctrl:1
	v_add_f32_e32 v18, v41, v51
	v_add_f32_dpp v57, v12, v12 quad_perm:[1,0,3,2] row_mask:0xf bank_mask:0xf bound_ctrl:1
	v_add_f32_e32 v12, v23, v24
	v_add_f32_dpp v53, v18, v18 quad_perm:[1,0,3,2] row_mask:0xf bank_mask:0xf bound_ctrl:1
	v_add_f32_e32 v18, v63, v68
	v_add_f32_dpp v62, v12, v12 quad_perm:[1,0,3,2] row_mask:0xf bank_mask:0xf bound_ctrl:1
	ds_read_b64_tr_b16 v[10:11], v40 offset:39168
	ds_read_b64_tr_b16 v[12:13], v40 offset:41472
	ds_read_b64_tr_b16 v[14:15], v40 offset:43776
	ds_read_b64_tr_b16 v[8:9], v40 offset:36864
	ds_read_b64_tr_b16 v[22:23], v40 offset:36896
	ds_read_b64_tr_b16 v[64:65], v40 offset:36928
	ds_read_b64_tr_b16 v[76:77], v40 offset:36960
	ds_read_b64_tr_b16 v[24:25], v40 offset:39200
	ds_read_b64_tr_b16 v[66:67], v40 offset:39232
	ds_read_b64_tr_b16 v[78:79], v40 offset:39264
	ds_read_b64_tr_b16 v[80:81], v40 offset:41504
	ds_read_b64_tr_b16 v[84:85], v40 offset:41536
	ds_read_b64_tr_b16 v[88:89], v40 offset:41568
	s_waitcnt lgkmcnt(9)
	v_mfma_f32_16x16x32_bf16 v[8:11], v[8:11], v[26:29], 0
	ds_read_b64_tr_b16 v[82:83], v40 offset:43808
	ds_read_b64_tr_b16 v[86:87], v40 offset:43840
	ds_read_b64_tr_b16 v[90:91], v40 offset:43872
	v_add_f32_dpp v63, v18, v18 quad_perm:[1,0,3,2] row_mask:0xf bank_mask:0xf bound_ctrl:1
	v_add_f32_e32 v18, v69, v71
	v_mfma_f32_16x16x32_bf16 v[8:11], v[12:15], v[72:75], v[8:11]
	v_mov_b32_e32 v54, 0
	v_mov_b32_e32 v59, 0
	v_mov_b32_e32 v70, 0
	s_waitcnt lgkmcnt(8)
	v_mfma_f32_16x16x32_bf16 v[12:15], v[22:25], v[26:29], 0
	v_mov_b32_e32 v61, 0
	v_mov_b32_e32 v55, 0
	v_lshlrev_b32_e32 v50, 1, v43
	s_waitcnt lgkmcnt(7)
	v_mfma_f32_16x16x32_bf16 v[22:25], v[64:67], v[26:29], 0
	v_mov_b32_e32 v64, 0
	v_add_f32_dpp v65, v18, v18 quad_perm:[1,0,3,2] row_mask:0xf bank_mask:0xf bound_ctrl:1
	v_mov_b32_e32 v66, 0
	s_waitcnt lgkmcnt(6)
	v_mfma_f32_16x16x32_bf16 v[26:29], v[76:79], v[26:29], 0
	s_add_i32 s56, s79, -2
	v_mov_b32_e32 v35, 0
	v_mov_b32_dpp v58, v56 quad_perm:[2,3,0,1] row_mask:0xf bank_mask:0xf
	s_waitcnt lgkmcnt(2)
	v_mfma_f32_16x16x32_bf16 v[12:15], v[80:83], v[72:75], v[12:15]
	v_mov_b32_dpp v54, v52 quad_perm:[2,3,0,1] row_mask:0xf bank_mask:0xf
	v_mov_b32_dpp v59, v57 quad_perm:[2,3,0,1] row_mask:0xf bank_mask:0xf
	v_mov_b32_dpp v70, v62 quad_perm:[2,3,0,1] row_mask:0xf bank_mask:0xf
	s_waitcnt lgkmcnt(1)
	v_mfma_f32_16x16x32_bf16 v[22:25], v[84:87], v[72:75], v[22:25]
	v_mov_b32_dpp v61, v60 quad_perm:[2,3,0,1] row_mask:0xf bank_mask:0xf
	v_mov_b32_dpp v55, v53 quad_perm:[2,3,0,1] row_mask:0xf bank_mask:0xf
	v_mov_b32_dpp v64, v63 quad_perm:[2,3,0,1] row_mask:0xf bank_mask:0xf
	s_waitcnt lgkmcnt(0)
	v_mfma_f32_16x16x32_bf16 v[26:29], v[88:91], v[72:75], v[26:29]
	v_mov_b32_dpp v66, v65 quad_perm:[2,3,0,1] row_mask:0xf bank_mask:0xf
	s_and_b64 vcc, exec, s[42:43]
	s_cbranch_vccz .LBB0_930
	ds_read_b128 v[72:75], v38 offset:9216
	ds_read_b128 v[76:79], v38 offset:9280
	ds_read_b128 v[80:83], v38 offset:11520
	ds_read_b128 v[84:87], v38 offset:11584
	ds_read_b128 v[88:91], v38 offset:13824
	ds_read_b128 v[92:95], v38 offset:13888
	ds_read_b128 v[96:99], v38 offset:16128
	ds_read_b128 v[100:103], v38 offset:16192
	v_or_b32_e32 v18, 0x42, v153
	s_waitcnt lgkmcnt(7)
	v_mfma_f32_16x16x32_bf16 v[72:75], v[72:75], v[4:7], 0
	v_or_b32_e32 v21, 64, v153
	v_cmp_lt_i32_e32 vcc, v18, v20
	v_or_b32_e32 v33, 0x43, v153
	s_waitcnt lgkmcnt(6)
	v_mfma_f32_16x16x32_bf16 v[72:75], v[76:79], v[0:3], v[72:75]
	v_or_b32_e32 v37, 0x41, v153
	v_or_b32_e32 v51, 0x50, v153
	v_or_b32_e32 v71, 0x51, v153
	s_waitcnt lgkmcnt(5)
	v_mfma_f32_16x16x32_bf16 v[80:83], v[80:83], v[4:7], 0
	v_mov_b32_e32 v116, v17
	s_nop 1
	v_fma_f32 v41, v72, s70, -v19
	v_exp_f32_e32 v68, v41
	v_fma_f32 v41, v73, s70, -v19
	s_waitcnt lgkmcnt(4)
	v_mfma_f32_16x16x32_bf16 v[76:79], v[84:87], v[0:3], v[80:83]
	v_exp_f32_e32 v84, v41
	v_fma_f32 v41, v74, s70, -v19
	v_exp_f32_e32 v69, v41
	s_waitcnt lgkmcnt(3)
	v_mfma_f32_16x16x32_bf16 v[80:83], v[88:91], v[4:7], 0
	v_fma_f32 v41, v75, s70, -v19
	s_nop 1
	v_fma_f32 v77, v77, s70, -v19
	v_exp_f32_e32 v85, v41
	s_waitcnt lgkmcnt(1)
	v_mfma_f32_16x16x32_bf16 v[72:75], v[96:99], v[4:7], 0
	v_exp_f32_e32 v86, v77
	v_fma_f32 v77, v78, s70, -v19
	v_fma_f32 v78, v79, s70, -v19
	v_mfma_f32_16x16x32_bf16 v[80:83], v[92:95], v[0:3], v[80:83]
	v_exp_f32_e32 v87, v78
	v_pk_mul_f32 v[68:69], v[16:17], v[68:69] op_sel_hi:[0,1]
	v_fma_f32 v67, v76, s70, -v19
	s_waitcnt lgkmcnt(0)
	v_mfma_f32_16x16x32_bf16 v[72:75], v[100:103], v[0:3], v[72:75]
	v_exp_f32_e32 v76, v67
	s_nop 1
	v_fma_f32 v79, v81, s70, -v19
	v_fma_f32 v78, v80, s70, -v19
	v_exp_f32_e32 v80, v79
	v_fma_f32 v79, v82, s70, -v19
	s_nop 0
	v_fma_f32 v72, v72, s70, -v19
	v_exp_f32_e32 v82, v72
	v_fma_f32 v72, v73, s70, -v19
	v_exp_f32_e32 v88, v72
	v_fma_f32 v72, v74, s70, -v19
	v_fma_f32 v81, v83, s70, -v19
	v_exp_f32_e32 v83, v72
	v_fma_f32 v72, v75, s70, -v19
	v_cndmask_b32_e32 v75, 0, v69, vcc
	v_cmp_lt_i32_e32 vcc, v21, v20
	v_exp_f32_e32 v89, v72
	v_mov_b32_e32 v72, v17
	v_cndmask_b32_e32 v74, 0, v68, vcc
	v_pk_mul_f32 v[68:69], v[16:17], v[84:85] op_sel_hi:[0,1]
	v_cmp_lt_i32_e32 vcc, v33, v20
	v_mov_b32_e32 v73, v17
	v_exp_f32_e32 v77, v77
	v_cndmask_b32_e32 v85, 0, v69, vcc
	v_cmp_lt_i32_e32 vcc, v37, v20
	v_or_b32_e32 v91, 32, v50
	v_or_b32_e32 v90, 33, v50
	v_cndmask_b32_e32 v84, 0, v68, vcc
	v_pk_add_f32 v[68:69], v[74:75], v[84:85]
	v_cmp_ge_u32_e32 vcc, s56, v91
	v_or_b32_e32 v41, 0x52, v153
	v_mov_b32_dpp v72, v68 quad_perm:[1,0,3,2] row_mask:0xf bank_mask:0xf
	v_mov_b32_dpp v73, v69 quad_perm:[1,0,3,2] row_mask:0xf bank_mask:0xf
	v_pk_add_f32 v[68:69], v[68:69], v[72:73]
	v_mov_b32_e32 v72, v17
	v_mov_b32_e32 v73, v17
	v_or_b32_e32 v67, 0x53, v153
	v_mov_b32_dpp v72, v68 quad_perm:[2,3,0,1] row_mask:0xf bank_mask:0xf
	v_mov_b32_dpp v73, v69 quad_perm:[2,3,0,1] row_mask:0xf bank_mask:0xf
	v_pk_add_f32 v[68:69], v[68:69], v[72:73]
	v_pk_mul_f32 v[72:73], v[16:17], v[76:77] op_sel_hi:[0,1]
	v_and_b32_e32 v21, 0xffffff80, v68
	v_and_b32_e32 v18, 0xffffff80, v69
	v_or_b32_e32 v21, v21, v50
	v_or_b32_e32 v18, v18, v50
	v_xor_b32_e32 v21, 0x5f, v21
	v_xor_b32_e32 v18, 0x5e, v18
	v_cndmask_b32_e32 v68, 0, v21, vcc
	v_cmp_ge_u32_e32 vcc, s56, v90
	v_mov_b32_e32 v90, v17
	v_mov_b32_e32 v91, v17
	v_cndmask_b32_e32 v69, 0, v18, vcc
	v_cmp_lt_i32_e32 vcc, v41, v20
	v_exp_f32_e32 v78, v78
	v_exp_f32_e32 v79, v79
	v_cndmask_b32_e32 v77, 0, v73, vcc
	v_cmp_lt_i32_e32 vcc, v51, v20
	v_or_b32_e32 v21, 40, v50
	v_exp_f32_e32 v81, v81
	v_cndmask_b32_e32 v76, 0, v72, vcc
	v_pk_mul_f32 v[72:73], v[16:17], v[86:87] op_sel_hi:[0,1]
	v_cmp_lt_i32_e32 vcc, v67, v20
	v_or_b32_e32 v18, 41, v50
	v_or_b32_e32 v92, 0x62, v153
	v_cndmask_b32_e32 v87, 0, v73, vcc
	v_cmp_lt_i32_e32 vcc, v71, v20
	v_or_b32_e32 v93, 0x60, v153
	v_pk_mul_f32 v[78:79], v[16:17], v[78:79] op_sel_hi:[0,1]
	v_cndmask_b32_e32 v86, 0, v72, vcc
	v_pk_add_f32 v[72:73], v[76:77], v[86:87]
	v_cmp_ge_u32_e32 vcc, s56, v21
	v_or_b32_e32 v94, 0x63, v153
	v_mov_b32_dpp v90, v72 quad_perm:[1,0,3,2] row_mask:0xf bank_mask:0xf
	v_mov_b32_dpp v91, v73 quad_perm:[1,0,3,2] row_mask:0xf bank_mask:0xf
	v_pk_add_f32 v[72:73], v[72:73], v[90:91]
	v_mov_b32_e32 v90, v17
	v_mov_b32_e32 v91, v17
	v_or_b32_e32 v95, 0x61, v153
	v_mov_b32_dpp v90, v72 quad_perm:[2,3,0,1] row_mask:0xf bank_mask:0xf
	v_mov_b32_dpp v91, v73 quad_perm:[2,3,0,1] row_mask:0xf bank_mask:0xf
	v_pk_add_f32 v[72:73], v[72:73], v[90:91]
	v_pk_mul_f32 v[80:81], v[16:17], v[80:81] op_sel_hi:[0,1]
	v_and_b32_e32 v37, 0xffffff80, v72
	v_and_b32_e32 v33, 0xffffff80, v73
	v_or_b32_e32 v37, v37, v50
	v_or_b32_e32 v33, v33, v50
	v_xor_b32_e32 v37, 0x57, v37
	v_xor_b32_e32 v33, 0x56, v33
	v_cndmask_b32_e32 v73, 0, v37, vcc
	v_cmp_ge_u32_e32 vcc, s56, v18
	v_or_b32_e32 v21, 48, v50
	v_or_b32_e32 v18, 49, v50
	v_cndmask_b32_e32 v33, 0, v33, vcc
	v_cmp_lt_i32_e32 vcc, v92, v20
	v_mov_b32_e32 v92, v17
	v_or_b32_e32 v96, 0x72, v153
	v_cndmask_b32_e32 v79, 0, v79, vcc
	v_cmp_lt_i32_e32 vcc, v93, v20
	v_mov_b32_e32 v93, v17
	v_or_b32_e32 v97, 0x70, v153
	v_cndmask_b32_e32 v78, 0, v78, vcc
	v_cmp_lt_i32_e32 vcc, v94, v20
	v_pk_mul_f32 v[82:83], v[16:17], v[82:83] op_sel_hi:[0,1]
	v_or_b32_e32 v98, 0x73, v153
	v_cndmask_b32_e32 v81, 0, v81, vcc
	v_cmp_lt_i32_e32 vcc, v95, v20
	v_or_b32_e32 v99, 0x71, v153
	v_pk_mul_f32 v[88:89], v[16:17], v[88:89] op_sel_hi:[0,1]
	v_cndmask_b32_e32 v80, 0, v80, vcc
	v_pk_add_f32 v[90:91], v[78:79], v[80:81]
	v_cmp_ge_u32_e32 vcc, s56, v21
	v_cvt_pk_bf16_f32 v74, v74, v84
	v_cvt_pk_bf16_f32 v75, v75, v85
	v_cvt_pk_bf16_f32 v76, v76, v86
	v_cvt_pk_bf16_f32 v77, v77, v87
	s_nop 0
	v_mov_b32_dpp v92, v90 quad_perm:[1,0,3,2] row_mask:0xf bank_mask:0xf
	v_mov_b32_dpp v93, v91 quad_perm:[1,0,3,2] row_mask:0xf bank_mask:0xf
	v_pk_add_f32 v[90:91], v[90:91], v[92:93]
	v_mov_b32_e32 v92, v17
	v_mov_b32_e32 v93, v17
	v_cvt_pk_bf16_f32 v78, v78, v80
	v_cvt_pk_bf16_f32 v79, v79, v81
	v_mov_b32_e32 v117, v17
	v_mov_b32_dpp v92, v90 quad_perm:[2,3,0,1] row_mask:0xf bank_mask:0xf
	v_mov_b32_dpp v93, v91 quad_perm:[2,3,0,1] row_mask:0xf bank_mask:0xf
	v_pk_add_f32 v[90:91], v[90:91], v[92:93]
	v_or_b32_e32 v21, 56, v50
	v_and_b32_e32 v41, 0xffffff80, v90
	v_and_b32_e32 v37, 0xffffff80, v91
	v_or_b32_e32 v41, v41, v50
	v_or_b32_e32 v37, v37, v50
	v_xor_b32_e32 v41, 0x4f, v41
	v_xor_b32_e32 v37, 0x4e, v37
	v_cndmask_b32_e32 v71, 0, v41, vcc
	v_cmp_ge_u32_e32 vcc, s56, v18
	v_or_b32_e32 v18, 57, v50
	s_nop 0
	v_cndmask_b32_e32 v72, 0, v37, vcc
	v_cmp_lt_i32_e32 vcc, v96, v20
	s_nop 1
	v_cndmask_b32_e32 v83, 0, v83, vcc
	v_cmp_lt_i32_e32 vcc, v97, v20
	s_nop 1
	v_cndmask_b32_e32 v82, 0, v82, vcc
	v_cmp_lt_i32_e32 vcc, v98, v20
	s_nop 1
	v_cndmask_b32_e32 v89, 0, v89, vcc
	v_cmp_lt_i32_e32 vcc, v99, v20
	s_nop 1
	v_cndmask_b32_e32 v88, 0, v88, vcc
	v_cvt_pk_bf16_f32 v80, v82, v88
	v_cvt_pk_bf16_f32 v81, v83, v89
	v_pk_add_f32 v[114:115], v[82:83], v[88:89]
	ds_read_b64_tr_b16 v[84:85], v40 offset:48384
	ds_read_b64_tr_b16 v[86:87], v40 offset:50688
	ds_read_b64_tr_b16 v[88:89], v40 offset:52992
	ds_read_b64_tr_b16 v[82:83], v40 offset:46080
	ds_read_b64_tr_b16 v[90:91], v40 offset:46112
	ds_read_b64_tr_b16 v[94:95], v40 offset:46144
	ds_read_b64_tr_b16 v[98:99], v40 offset:46176
	ds_read_b64_tr_b16 v[92:93], v40 offset:48416
	ds_read_b64_tr_b16 v[96:97], v40 offset:48448
	ds_read_b64_tr_b16 v[100:101], v40 offset:48480
	ds_read_b64_tr_b16 v[102:103], v40 offset:50720
	ds_read_b64_tr_b16 v[106:107], v40 offset:50752
	ds_read_b64_tr_b16 v[110:111], v40 offset:50784
	ds_read_b64_tr_b16 v[104:105], v40 offset:53024
	ds_read_b64_tr_b16 v[108:109], v40 offset:53056
	ds_read_b64_tr_b16 v[112:113], v40 offset:53088
	v_mov_b32_dpp v116, v114 quad_perm:[1,0,3,2] row_mask:0xf bank_mask:0xf
	v_mov_b32_dpp v117, v115 quad_perm:[1,0,3,2] row_mask:0xf bank_mask:0xf
	s_waitcnt lgkmcnt(12)
	v_mfma_f32_16x16x32_bf16 v[8:11], v[82:85], v[74:77], v[8:11]
	v_add_f32_e64 v82, v114, v116
	v_add_f32_e64 v83, v115, v117
	v_mov_b32_e32 v84, v17
	v_mov_b32_e32 v85, v17
	s_waitcnt lgkmcnt(8)
	v_mfma_f32_16x16x32_bf16 v[12:15], v[90:93], v[74:77], v[12:15]
	v_mov_b32_dpp v84, v82 quad_perm:[2,3,0,1] row_mask:0xf bank_mask:0xf
	v_mov_b32_dpp v85, v83 quad_perm:[2,3,0,1] row_mask:0xf bank_mask:0xf
	v_pk_add_f32 v[82:83], v[82:83], v[84:85]
	s_waitcnt lgkmcnt(7)
	v_mfma_f32_16x16x32_bf16 v[22:25], v[94:97], v[74:77], v[22:25]
	v_and_b32_e32 v41, 0xffffff80, v82
	v_and_b32_e32 v37, 0xffffff80, v83
	v_or_b32_e32 v41, v41, v50
	s_waitcnt lgkmcnt(6)
	v_mfma_f32_16x16x32_bf16 v[26:29], v[98:101], v[74:77], v[26:29]
	v_or_b32_e32 v37, v37, v50
	v_xor_b32_e32 v41, 0x47, v41
	v_cmp_ge_u32_e32 vcc, s56, v21
	v_mfma_f32_16x16x32_bf16 v[8:11], v[86:89], v[78:81], v[8:11]
	v_xor_b32_e32 v37, 0x46, v37
	v_cndmask_b32_e32 v75, 0, v41, vcc
	v_cmp_ge_u32_e32 vcc, s56, v18
	s_waitcnt lgkmcnt(2)
	v_mfma_f32_16x16x32_bf16 v[12:15], v[102:105], v[78:81], v[12:15]
	v_cndmask_b32_e32 v37, 0, v37, vcc
	s_waitcnt lgkmcnt(1)
	v_mfma_f32_16x16x32_bf16 v[22:25], v[106:109], v[78:81], v[22:25]
	s_waitcnt lgkmcnt(0)
	v_mfma_f32_16x16x32_bf16 v[26:29], v[110:113], v[78:81], v[26:29]
	s_branch .LBB0_931

.LBB0_1027:
	ds_read_b128 v[12:15], v9
	ds_read_b128 v[22:25], v9 offset:64
	ds_read_b128 v[26:29], v9 offset:2304
	ds_read_b128 v[52:55], v9 offset:2368
	ds_read_b128 v[56:59], v9 offset:4608
	ds_read_b128 v[60:63], v9 offset:4672
	ds_read_b128 v[64:67], v9 offset:6912
	ds_read_b128 v[68:71], v9 offset:6976
	s_waitcnt vmcnt(1) lgkmcnt(7)
	v_mfma_f32_16x16x32_bf16 v[12:15], v[12:15], v[4:7], 0
	v_add_u32_e32 v10, s22, v153
	v_cmp_lt_i32_e32 vcc, v10, v35
	s_add_i32 s22, s22, 64
	s_waitcnt vmcnt(0) lgkmcnt(6)
	v_mfma_f32_16x16x32_bf16 v[12:15], v[22:25], v[0:3], v[12:15]
	v_add_u32_e32 v9, 0x2400, v9
	s_cmp_eq_u32 s76, s22
	s_waitcnt lgkmcnt(5)
	v_mfma_f32_16x16x32_bf16 v[22:25], v[26:29], v[4:7], 0
	s_waitcnt lgkmcnt(3)
	v_mfma_f32_16x16x32_bf16 v[26:29], v[56:59], v[4:7], 0
	s_nop 1
	v_cndmask_b32_e32 v56, v246, v12, vcc
	v_add_u32_e32 v12, 1, v10
	v_cmp_lt_i32_e32 vcc, v12, v35
	v_mfma_f32_16x16x32_bf16 v[22:25], v[52:55], v[0:3], v[22:25]
	s_nop 0
	v_cndmask_b32_e32 v57, v246, v13, vcc
	v_add_u32_e32 v13, 2, v10
	v_cmp_lt_i32_e32 vcc, v13, v35
	v_add_u32_e32 v13, 3, v10
	s_waitcnt lgkmcnt(2)
	v_mfma_f32_16x16x32_bf16 v[26:29], v[60:63], v[0:3], v[26:29]
	v_cndmask_b32_e32 v14, v246, v14, vcc
	v_cmp_lt_i32_e32 vcc, v13, v35
	v_add_u32_e32 v13, 16, v10
	s_waitcnt lgkmcnt(1)
	v_mfma_f32_16x16x32_bf16 v[52:55], v[64:67], v[4:7], 0
	v_cndmask_b32_e32 v15, v246, v15, vcc
	v_cmp_lt_i32_e32 vcc, v13, v35
	v_add_u32_e32 v13, 17, v10
	s_waitcnt lgkmcnt(0)
	v_mfma_f32_16x16x32_bf16 v[52:55], v[68:71], v[0:3], v[52:55]
	v_cndmask_b32_e32 v22, v246, v22, vcc
	v_cmp_lt_i32_e32 vcc, v13, v35
	v_add_u32_e32 v13, 18, v10
	v_max3_f32 v12, v56, s96, v57
	v_cndmask_b32_e32 v23, v246, v23, vcc
	v_cmp_lt_i32_e32 vcc, v13, v35
	v_add_u32_e32 v13, 19, v10
	v_max3_f32 v12, v12, v14, v15
	v_cndmask_b32_e32 v24, v246, v24, vcc
	v_cmp_lt_i32_e32 vcc, v13, v35
	v_add_u32_e32 v13, 32, v10
	v_max3_f32 v12, v12, v22, v23
	v_cndmask_b32_e32 v25, v246, v25, vcc
	v_cmp_lt_i32_e32 vcc, v13, v35
	v_add_u32_e32 v13, 33, v10
	v_max3_f32 v12, v12, v24, v25
	v_cndmask_b32_e32 v26, v246, v26, vcc
	v_cmp_lt_i32_e32 vcc, v13, v35
	v_add_u32_e32 v13, 34, v10
	s_nop 0
	v_cndmask_b32_e32 v27, v246, v27, vcc
	v_cmp_lt_i32_e32 vcc, v13, v35
	v_add_u32_e32 v13, 35, v10
	v_max3_f32 v12, v12, v26, v27
	v_cndmask_b32_e32 v28, v246, v28, vcc
	v_cmp_lt_i32_e32 vcc, v13, v35
	v_add_u32_e32 v13, 48, v10
	s_nop 0
	v_cndmask_b32_e32 v29, v246, v29, vcc
	v_cmp_lt_i32_e32 vcc, v13, v35
	v_add_u32_e32 v13, 49, v10
	v_max3_f32 v12, v12, v28, v29
	v_cndmask_b32_e32 v52, v246, v52, vcc
	v_cmp_lt_i32_e32 vcc, v13, v35
	s_nop 1
	v_cndmask_b32_e32 v53, v246, v53, vcc
	v_max3_f32 v13, v12, v52, v53
	v_add_u32_e32 v12, 50, v10
	v_cmp_lt_i32_e32 vcc, v12, v35
	v_add_u32_e32 v10, 51, v10
	s_nop 0
	v_cndmask_b32_e32 v54, v246, v54, vcc
	v_cmp_lt_i32_e32 vcc, v10, v35
	s_nop 1
	v_cndmask_b32_e32 v12, v246, v55, vcc
	v_max3_f32 v10, v13, v54, v12
	v_mov_b32_e32 v13, v10
	s_nop 1
	v_permlane16_swap_b32_e32 v10, v13
	v_max_f32_e32 v13, v13, v13
	v_max_f32_e32 v10, v10, v10
	v_max_f32_e32 v10, v10, v13
	v_mov_b32_e32 v13, v10
	s_nop 1
	v_permlane32_swap_b32_e32 v10, v13
	v_max3_f32 v10, v11, v10, v13
	v_max_f32_e32 v13, 0xe0ad78ec, v10
	v_pk_mul_f32 v[36:37], v[12:13], s[70:71] op_sel_hi:[1,0]
	v_sub_f32_e32 v11, v11, v10
	v_fma_f32 v12, v56, s70, -v37
	v_exp_f32_e32 v12, v12
	v_fma_f32 v13, v57, s70, -v37
	v_exp_f32_e32 v13, v13
	v_mul_f32_e32 v11, 0x3e38aa3b, v11
	v_add_f32_e32 v12, 0, v12
	v_exp_f32_e32 v11, v11
	v_add_f32_e32 v12, v13, v12
	v_fma_f32 v13, v14, s70, -v37
	v_exp_f32_e32 v13, v13
	s_nop 0
	v_add_f32_e32 v12, v13, v12
	v_fma_f32 v13, v15, s70, -v37
	v_exp_f32_e32 v13, v13
	s_nop 0
	v_add_f32_e32 v12, v13, v12
	v_fma_f32 v13, v22, s70, -v37
	v_exp_f32_e32 v13, v13
	s_nop 0
	v_add_f32_e32 v12, v13, v12
	v_fma_f32 v13, v23, s70, -v37
	v_exp_f32_e32 v13, v13
	s_nop 0
	v_add_f32_e32 v12, v13, v12
	v_fma_f32 v13, v24, s70, -v37
	v_exp_f32_e32 v13, v13
	s_nop 0
	v_add_f32_e32 v12, v13, v12
	v_fma_f32 v13, v25, s70, -v37
	v_exp_f32_e32 v13, v13
	s_nop 0
	v_add_f32_e32 v12, v13, v12
	v_fma_f32 v13, v26, s70, -v37
	v_exp_f32_e32 v13, v13
	s_nop 0
	v_add_f32_e32 v12, v13, v12
	v_fma_f32 v13, v27, s70, -v37
	v_exp_f32_e32 v13, v13
	s_nop 0
	v_add_f32_e32 v12, v13, v12
	v_fma_f32 v13, v28, s70, -v37
	v_exp_f32_e32 v13, v13
	s_nop 0
	v_add_f32_e32 v12, v13, v12
	v_fma_f32 v13, v29, s70, -v37
	v_exp_f32_e32 v13, v13
	s_nop 0
	v_add_f32_e32 v12, v13, v12
	v_fma_f32 v13, v52, s70, -v37
	v_exp_f32_e32 v13, v13
	s_nop 0
	v_add_f32_e32 v12, v13, v12
	v_fma_f32 v13, v53, s70, -v37
	v_exp_f32_e32 v13, v13
	s_nop 0
	v_add_f32_e32 v12, v13, v12
	v_fma_f32 v13, v54, s70, -v37
	v_exp_f32_e32 v13, v13
	s_nop 0
	v_add_f32_e32 v12, v13, v12
	v_sub_f32_e32 v13, v36, v37
	v_exp_f32_e32 v13, v13
	s_nop 0
	v_add_f32_e32 v12, v13, v12
	v_mov_b32_e32 v13, v8
	v_mov_b32_e32 v8, v12
	v_fmac_f32_e32 v8, v13, v11
	v_mov_b32_e32 v11, v10
	s_cbranch_scc0 .LBB0_1027
	ds_read_b128 v[10:13], v38
	ds_read_b128 v[22:25], v38 offset:64
	v_mov_b32_e32 v9, v8
	s_nop 1
	v_permlane16_swap_b32_e32 v8, v9
	v_add_f32_e32 v8, v8, v9
	v_mov_b32_e32 v9, v8
	s_nop 1
	v_permlane32_swap_b32_e32 v8, v9
	v_add_f32_e32 v8, v8, v9
	v_max_f32_e32 v36, 0xda24260, v8
	s_waitcnt lgkmcnt(1)
	v_mfma_f32_16x16x32_bf16 v[8:11], v[10:13], v[4:7], 0
	ds_read_b128 v[26:29], v38 offset:2304
	ds_read_b128 v[12:15], v38 offset:2368
	v_div_scale_f32 v60, s[22:23], v36, v36, 1.0
	v_rcp_f32_e32 v61, v60
	s_waitcnt lgkmcnt(2)
	v_mfma_f32_16x16x32_bf16 v[8:11], v[22:25], v[0:3], v[8:11]
	ds_read_b128 v[22:25], v38 offset:4608
	v_div_scale_f32 v62, vcc, 1.0, v36, 1.0
	v_fma_f32 v52, -v60, v61, 1.0
	v_fmac_f32_e32 v61, v52, v61
	ds_read_b128 v[52:55], v38 offset:4672
	s_waitcnt lgkmcnt(3)
	v_mfma_f32_16x16x32_bf16 v[26:29], v[26:29], v[4:7], 0
	v_mul_f32_e32 v63, v62, v61
	v_fma_f32 v56, -v60, v63, v62
	v_pk_fma_f32 v[8:9], v[8:9], s[70:71], v[36:37] op_sel:[0,0,1] op_sel_hi:[1,0,1] neg_lo:[0,0,1] neg_hi:[0,0,1]
	s_waitcnt lgkmcnt(1)
	v_mfma_f32_16x16x32_bf16 v[22:25], v[22:25], v[4:7], 0
	v_fmac_f32_e32 v63, v56, v61
	v_exp_f32_e32 v8, v8
	v_mfma_f32_16x16x32_bf16 v[12:15], v[12:15], v[0:3], v[26:29]
	v_exp_f32_e32 v9, v9
	v_pk_fma_f32 v[10:11], v[10:11], s[70:71], v[36:37] op_sel:[0,0,1] op_sel_hi:[1,0,1] neg_lo:[0,0,1] neg_hi:[0,0,1]
	v_exp_f32_e32 v10, v10
	s_waitcnt lgkmcnt(0)
	v_mfma_f32_16x16x32_bf16 v[22:25], v[52:55], v[0:3], v[22:25]
	v_fma_f32 v52, -v60, v63, v62
	ds_read_b128 v[26:29], v38 offset:6912
	ds_read_b128 v[56:59], v38 offset:6976
	v_div_fmas_f32 v52, v52, v61, v63
	v_div_fixup_f32 v36, v52, v36, 1.0
	v_exp_f32_e32 v11, v11
	v_pk_fma_f32 v[12:13], v[12:13], s[70:71], v[36:37] op_sel:[0,0,1] op_sel_hi:[1,0,1] neg_lo:[0,0,1] neg_hi:[0,0,1]
	v_mul_f32_e32 v8, v36, v8
	v_cmp_lt_i32_e32 vcc, v153, v35
	v_exp_f32_e32 v12, v12
	v_cndmask_b32_e32 v8, 0, v8, vcc
	v_mul_f32_e32 v9, v36, v9
	v_cmp_lt_i32_e32 vcc, v154, v35
	v_exp_f32_e32 v13, v13
	v_pk_fma_f32 v[14:15], v[14:15], s[70:71], v[36:37] op_sel:[0,0,1] op_sel_hi:[1,0,1] neg_lo:[0,0,1] neg_hi:[0,0,1]
	v_cndmask_b32_e32 v9, 0, v9, vcc
	v_mul_f32_e32 v10, v36, v10
	v_cmp_lt_i32_e32 vcc, v155, v35
	v_exp_f32_e32 v14, v14
	v_cndmask_b32_e32 v10, 0, v10, vcc
	v_mul_f32_e32 v11, v36, v11
	v_cmp_lt_i32_e32 vcc, v156, v35
	v_exp_f32_e32 v15, v15
	v_pk_fma_f32 v[22:23], v[22:23], s[70:71], v[36:37] op_sel:[0,0,1] op_sel_hi:[1,0,1] neg_lo:[0,0,1] neg_hi:[0,0,1]
	v_cndmask_b32_e32 v11, 0, v11, vcc
	v_mul_f32_e32 v12, v36, v12
	v_cmp_lt_i32_e32 vcc, v158, v35
	v_exp_f32_e32 v22, v22
	v_cndmask_b32_e32 v12, 0, v12, vcc
	v_mul_f32_e32 v13, v36, v13
	v_cmp_lt_i32_e32 vcc, v159, v35
	v_exp_f32_e32 v23, v23
	v_mul_f32_e32 v14, v36, v14
	v_cndmask_b32_e32 v13, 0, v13, vcc
	v_cmp_lt_i32_e32 vcc, v160, v35
	s_waitcnt lgkmcnt(1)
	v_mfma_f32_16x16x32_bf16 v[26:29], v[26:29], v[4:7], 0
	v_mul_f32_e32 v15, v36, v15
	v_cndmask_b32_e32 v14, 0, v14, vcc
	v_cmp_lt_i32_e32 vcc, v161, v35
	v_mul_f32_e32 v22, v36, v22
	s_waitcnt lgkmcnt(0)
	v_mfma_f32_16x16x32_bf16 v[26:29], v[56:59], v[0:3], v[26:29]
	v_cndmask_b32_e32 v15, 0, v15, vcc
	v_cmp_lt_i32_e32 vcc, v162, v35
	v_mov_b32_e32 v63, 0
	v_mov_b32_e32 v58, 0
	v_cndmask_b32_e32 v52, 0, v22, vcc
	v_mul_f32_e32 v22, v36, v23
	v_fma_f32 v23, v24, s70, -v37
	v_cmp_lt_i32_e32 vcc, v163, v35
	v_exp_f32_e32 v23, v23
	v_mov_b32_e32 v64, 0
	v_cndmask_b32_e32 v54, 0, v22, vcc
	v_fma_f32 v22, v25, s70, -v37
	v_exp_f32_e32 v22, v22
	v_mul_f32_e32 v23, v36, v23
	v_cmp_lt_i32_e32 vcc, v164, v35
	v_mov_b32_e32 v74, 0
	v_mul_f32_e32 v22, v36, v22
	v_cndmask_b32_e32 v55, 0, v23, vcc
	v_fma_f32 v23, v26, s70, -v37
	v_cmp_lt_i32_e32 vcc, v165, v35
	v_exp_f32_e32 v23, v23
	v_mov_b32_e32 v62, 0
	v_cndmask_b32_e32 v56, 0, v22, vcc
	v_fma_f32 v22, v27, s70, -v37
	v_exp_f32_e32 v22, v22
	v_mul_f32_e32 v23, v36, v23
	v_cmp_lt_i32_e32 vcc, v166, v35
	v_mov_b32_e32 v53, 0
	v_mul_f32_e32 v22, v36, v22
	v_cndmask_b32_e32 v75, 0, v23, vcc
	v_fma_f32 v23, v28, s70, -v37
	v_cmp_lt_i32_e32 vcc, v167, v35
	v_exp_f32_e32 v23, v23
	s_nop 0
	v_cndmask_b32_e32 v96, 0, v22, vcc
	v_fma_f32 v22, v29, s70, -v37
	v_exp_f32_e32 v22, v22
	v_mul_f32_e32 v23, v36, v23
	v_cmp_lt_i32_e32 vcc, v168, v35
	v_mul_f32_e32 v22, v36, v22
	s_nop 0
	v_cndmask_b32_e32 v97, 0, v23, vcc
	v_cmp_lt_i32_e32 vcc, v169, v35
	s_nop 1
	v_cndmask_b32_e32 v98, 0, v22, vcc
	v_add_f32_e32 v22, v8, v9
	s_and_b64 vcc, exec, s[42:43]
	s_nop 0
	v_add_f32_dpp v60, v22, v22 quad_perm:[1,0,3,2] row_mask:0xf bank_mask:0xf bound_ctrl:1
	v_add_f32_e32 v22, v10, v11
	s_nop 0
	v_mov_b32_dpp v63, v60 quad_perm:[2,3,0,1] row_mask:0xf bank_mask:0xf
	v_add_f32_dpp v57, v22, v22 quad_perm:[1,0,3,2] row_mask:0xf bank_mask:0xf bound_ctrl:1
	v_add_f32_e32 v22, v12, v13
	s_nop 0
	v_mov_b32_dpp v58, v57 quad_perm:[2,3,0,1] row_mask:0xf bank_mask:0xf
	v_add_f32_dpp v61, v22, v22 quad_perm:[1,0,3,2] row_mask:0xf bank_mask:0xf bound_ctrl:1
	v_add_f32_e32 v22, v14, v15
	s_nop 0
	v_mov_b32_dpp v64, v61 quad_perm:[2,3,0,1] row_mask:0xf bank_mask:0xf
	v_add_f32_dpp v65, v22, v22 quad_perm:[1,0,3,2] row_mask:0xf bank_mask:0xf bound_ctrl:1
	v_cvt_pk_bf16_f32 v22, v8, v9
	v_cvt_pk_bf16_f32 v23, v10, v11
	v_cvt_pk_bf16_f32 v24, v12, v13
	v_cvt_pk_bf16_f32 v25, v14, v15
	v_cvt_pk_bf16_f32 v70, v52, v54
	v_cvt_pk_bf16_f32 v71, v55, v56
	v_cvt_pk_bf16_f32 v72, v75, v96
	v_cvt_pk_bf16_f32 v73, v97, v98
	ds_read_b64_tr_b16 v[10:11], v40 offset:39168
	ds_read_b64_tr_b16 v[12:13], v40 offset:41472
	ds_read_b64_tr_b16 v[14:15], v40 offset:43776
	ds_read_b64_tr_b16 v[8:9], v40 offset:36864
	ds_read_b64_tr_b16 v[66:67], v40 offset:36896
	ds_read_b64_tr_b16 v[76:77], v40 offset:36928
	ds_read_b64_tr_b16 v[80:81], v40 offset:36960
	ds_read_b64_tr_b16 v[68:69], v40 offset:39200
	ds_read_b64_tr_b16 v[78:79], v40 offset:39232
	ds_read_b64_tr_b16 v[82:83], v40 offset:39264
	ds_read_b64_tr_b16 v[84:85], v40 offset:41504
	ds_read_b64_tr_b16 v[88:89], v40 offset:41536
	ds_read_b64_tr_b16 v[92:93], v40 offset:41568
	s_waitcnt lgkmcnt(9)
	v_mfma_f32_16x16x32_bf16 v[8:11], v[8:11], v[22:25], 0
	ds_read_b64_tr_b16 v[86:87], v40 offset:43808
	ds_read_b64_tr_b16 v[90:91], v40 offset:43840
	ds_read_b64_tr_b16 v[94:95], v40 offset:43872
	v_mov_b32_dpp v74, v65 quad_perm:[2,3,0,1] row_mask:0xf bank_mask:0xf
	v_mfma_f32_16x16x32_bf16 v[26:29], v[12:15], v[70:73], v[8:11]
	v_add_f32_e32 v12, v52, v54
	v_add_f32_e32 v52, v75, v96
	s_nop 0
	v_add_f32_dpp v59, v12, v12 quad_perm:[1,0,3,2] row_mask:0xf bank_mask:0xf bound_ctrl:1
	v_add_f32_e32 v12, v55, v56
	s_waitcnt lgkmcnt(8)
	v_mfma_f32_16x16x32_bf16 v[8:11], v[66:69], v[22:25], 0
	v_add_f32_dpp v66, v52, v52 quad_perm:[1,0,3,2] row_mask:0xf bank_mask:0xf bound_ctrl:1
	v_add_f32_dpp v55, v12, v12 quad_perm:[1,0,3,2] row_mask:0xf bank_mask:0xf bound_ctrl:1
	v_add_f32_e32 v52, v97, v98
	s_waitcnt lgkmcnt(7)
	v_mfma_f32_16x16x32_bf16 v[12:15], v[76:79], v[22:25], 0
	v_mov_b32_e32 v56, 0
	v_mov_b32_e32 v67, 0
	v_add_f32_dpp v68, v52, v52 quad_perm:[1,0,3,2] row_mask:0xf bank_mask:0xf bound_ctrl:1
	s_waitcnt lgkmcnt(6)
	v_mfma_f32_16x16x32_bf16 v[22:25], v[80:83], v[22:25], 0
	v_mov_b32_e32 v69, 0
	v_mov_b32_dpp v62, v59 quad_perm:[2,3,0,1] row_mask:0xf bank_mask:0xf
	v_mov_b32_dpp v56, v55 quad_perm:[2,3,0,1] row_mask:0xf bank_mask:0xf
	s_waitcnt lgkmcnt(2)
	v_mfma_f32_16x16x32_bf16 v[8:11], v[84:87], v[70:73], v[8:11]
	v_mov_b32_dpp v67, v66 quad_perm:[2,3,0,1] row_mask:0xf bank_mask:0xf
	v_mov_b32_dpp v69, v68 quad_perm:[2,3,0,1] row_mask:0xf bank_mask:0xf
	s_waitcnt lgkmcnt(1)
	v_mfma_f32_16x16x32_bf16 v[12:15], v[88:91], v[70:73], v[12:15]
	s_waitcnt lgkmcnt(0)
	v_mfma_f32_16x16x32_bf16 v[22:25], v[92:95], v[70:73], v[22:25]
	s_cbranch_vccz .LBB0_1030
	ds_read_b128 v[70:73], v38 offset:9216
	ds_read_b128 v[76:79], v38 offset:9280
	ds_read_b128 v[80:83], v38 offset:11520
	ds_read_b128 v[84:87], v38 offset:11584
	ds_read_b128 v[88:91], v38 offset:13824
	ds_read_b128 v[92:95], v38 offset:13888
	ds_read_b128 v[96:99], v38 offset:16128
	ds_read_b128 v[100:103], v38 offset:16192
	v_or_b32_e32 v52, 0x42, v153
	s_waitcnt lgkmcnt(7)
	v_mfma_f32_16x16x32_bf16 v[70:73], v[70:73], v[4:7], 0
	v_or_b32_e32 v54, 64, v153
	v_cmp_lt_i32_e32 vcc, v52, v35
	v_or_b32_e32 v75, 0x43, v153
	s_waitcnt lgkmcnt(6)
	v_mfma_f32_16x16x32_bf16 v[70:73], v[76:79], v[0:3], v[70:73]
	v_or_b32_e32 v104, 0x41, v153
	v_or_b32_e32 v106, 32, v50
	v_or_b32_e32 v105, 0x71, v153
	s_waitcnt lgkmcnt(5)
	v_mfma_f32_16x16x32_bf16 v[80:83], v[80:83], v[4:7], 0
	v_mov_b32_e32 v120, v17
	s_nop 1
	v_fma_f32 v70, v70, s70, -v37
	v_mov_b32_e32 v121, v17
	s_waitcnt lgkmcnt(4)
	v_mfma_f32_16x16x32_bf16 v[76:79], v[84:87], v[0:3], v[80:83]
	v_exp_f32_e32 v84, v70
	v_fma_f32 v70, v71, s70, -v37
	v_exp_f32_e32 v86, v70
	v_fma_f32 v70, v72, s70, -v37
	v_exp_f32_e32 v85, v70
	v_fma_f32 v70, v73, s70, -v37
	s_waitcnt lgkmcnt(3)
	v_mfma_f32_16x16x32_bf16 v[80:83], v[88:91], v[4:7], 0
	v_exp_f32_e32 v87, v70
	v_fma_f32 v77, v77, s70, -v37
	v_exp_f32_e32 v88, v77
	s_waitcnt lgkmcnt(1)
	v_mfma_f32_16x16x32_bf16 v[70:73], v[96:99], v[4:7], 0
	v_fma_f32 v77, v78, s70, -v37
	v_fma_f32 v78, v79, s70, -v37
	v_exp_f32_e32 v89, v78
	v_mfma_f32_16x16x32_bf16 v[80:83], v[92:95], v[0:3], v[80:83]
	v_fma_f32 v76, v76, s70, -v37
	v_exp_f32_e32 v76, v76
	v_exp_f32_e32 v77, v77
	s_waitcnt lgkmcnt(0)
	v_mfma_f32_16x16x32_bf16 v[70:73], v[100:103], v[0:3], v[70:73]
	v_or_b32_e32 v93, 33, v50
	s_nop 1
	v_fma_f32 v79, v81, s70, -v37
	v_fma_f32 v78, v80, s70, -v37
	v_exp_f32_e32 v80, v79
	v_fma_f32 v79, v82, s70, -v37
	s_nop 0
	v_fma_f32 v70, v70, s70, -v37
	v_exp_f32_e32 v82, v70
	v_fma_f32 v70, v71, s70, -v37
	v_exp_f32_e32 v90, v70
	v_fma_f32 v70, v72, s70, -v37
	v_fma_f32 v81, v83, s70, -v37
	v_exp_f32_e32 v83, v70
	v_fma_f32 v70, v73, s70, -v37
	v_exp_f32_e32 v91, v70
	v_pk_mul_f32 v[70:71], v[36:37], v[84:85] op_sel_hi:[0,1]
	v_cndmask_b32_e32 v85, 0, v71, vcc
	v_cmp_lt_i32_e32 vcc, v54, v35
	v_mov_b32_e32 v72, v17
	v_mov_b32_e32 v73, v17
	v_cndmask_b32_e32 v84, 0, v70, vcc
	v_pk_mul_f32 v[70:71], v[36:37], v[86:87] op_sel_hi:[0,1]
	v_cmp_lt_i32_e32 vcc, v75, v35
	v_or_b32_e32 v92, 0x52, v153
	v_or_b32_e32 v94, 0x50, v153
	v_cndmask_b32_e32 v87, 0, v71, vcc
	v_cmp_lt_i32_e32 vcc, v104, v35
	v_pk_mul_f32 v[76:77], v[36:37], v[76:77] op_sel_hi:[0,1]
	v_or_b32_e32 v95, 0x53, v153
	v_cndmask_b32_e32 v86, 0, v70, vcc
	v_pk_add_f32 v[70:71], v[84:85], v[86:87]
	v_cmp_ge_i32_e32 vcc, s56, v106
	v_or_b32_e32 v96, 0x51, v153
	v_mov_b32_dpp v72, v70 quad_perm:[1,0,3,2] row_mask:0xf bank_mask:0xf
	v_mov_b32_dpp v73, v71 quad_perm:[1,0,3,2] row_mask:0xf bank_mask:0xf
	v_pk_add_f32 v[70:71], v[70:71], v[72:73]
	v_mov_b32_e32 v72, v17
	v_mov_b32_e32 v73, v17
	v_exp_f32_e32 v78, v78
	v_mov_b32_dpp v72, v70 quad_perm:[2,3,0,1] row_mask:0xf bank_mask:0xf
	v_mov_b32_dpp v73, v71 quad_perm:[2,3,0,1] row_mask:0xf bank_mask:0xf
	v_pk_add_f32 v[70:71], v[70:71], v[72:73]
	v_exp_f32_e32 v79, v79
	v_and_b32_e32 v54, 0xffffff80, v70
	v_and_b32_e32 v52, 0xffffff80, v71
	v_or_b32_e32 v54, v54, v50
	v_or_b32_e32 v52, v52, v50
	v_xor_b32_e32 v54, 0x5f, v54
	v_xor_b32_e32 v52, 0x5e, v52
	v_cndmask_b32_e32 v71, 0, v54, vcc
	v_cmp_ge_i32_e32 vcc, s56, v93
	v_or_b32_e32 v54, 40, v50
	v_exp_f32_e32 v81, v81
	v_cndmask_b32_e32 v72, 0, v52, vcc
	v_cmp_lt_i32_e32 vcc, v92, v35
	v_or_b32_e32 v52, 41, v50
	v_or_b32_e32 v97, 0x62, v153
	v_cndmask_b32_e32 v93, 0, v77, vcc
	v_cmp_lt_i32_e32 vcc, v94, v35
	v_mov_b32_e32 v94, v17
	v_or_b32_e32 v98, 0x60, v153
	v_cndmask_b32_e32 v92, 0, v76, vcc
	v_pk_mul_f32 v[76:77], v[36:37], v[88:89] op_sel_hi:[0,1]
	v_cmp_lt_i32_e32 vcc, v95, v35
	v_mov_b32_e32 v95, v17
	v_pk_mul_f32 v[78:79], v[36:37], v[78:79] op_sel_hi:[0,1]
	v_cndmask_b32_e32 v89, 0, v77, vcc
	v_cmp_lt_i32_e32 vcc, v96, v35
	v_or_b32_e32 v99, 0x63, v153
	v_or_b32_e32 v100, 0x61, v153
	v_cndmask_b32_e32 v88, 0, v76, vcc
	v_pk_add_f32 v[76:77], v[92:93], v[88:89]
	v_cmp_ge_i32_e32 vcc, s56, v54
	v_or_b32_e32 v54, 49, v50
	v_mov_b32_dpp v94, v76 quad_perm:[1,0,3,2] row_mask:0xf bank_mask:0xf
	v_mov_b32_dpp v95, v77 quad_perm:[1,0,3,2] row_mask:0xf bank_mask:0xf
	v_pk_add_f32 v[76:77], v[76:77], v[94:95]
	v_mov_b32_e32 v94, v17
	v_mov_b32_e32 v95, v17
	v_or_b32_e32 v101, 0x72, v153
	v_mov_b32_dpp v94, v76 quad_perm:[2,3,0,1] row_mask:0xf bank_mask:0xf
	v_mov_b32_dpp v95, v77 quad_perm:[2,3,0,1] row_mask:0xf bank_mask:0xf
	v_pk_add_f32 v[76:77], v[76:77], v[94:95]
	v_or_b32_e32 v102, 0x70, v153
	v_and_b32_e32 v73, 0xffffff80, v76
	v_and_b32_e32 v70, 0xffffff80, v77
	v_or_b32_e32 v73, v73, v50
	v_or_b32_e32 v70, v70, v50
	v_xor_b32_e32 v73, 0x57, v73
	v_xor_b32_e32 v70, 0x56, v70
	v_cndmask_b32_e32 v76, 0, v73, vcc
	v_cmp_ge_i32_e32 vcc, s56, v52
	v_or_b32_e32 v103, 0x73, v153
	s_nop 0
	v_cndmask_b32_e32 v52, 0, v70, vcc
	v_cmp_lt_i32_e32 vcc, v97, v35
	v_or_b32_e32 v70, 48, v50
	s_nop 0
	v_cndmask_b32_e32 v95, 0, v79, vcc
	v_cmp_lt_i32_e32 vcc, v98, v35
	s_nop 1
	v_cndmask_b32_e32 v94, 0, v78, vcc
	v_pk_mul_f32 v[78:79], v[36:37], v[80:81] op_sel_hi:[0,1]
	v_cmp_lt_i32_e32 vcc, v99, v35
	v_mov_b32_e32 v80, v17
	v_mov_b32_e32 v81, v17
	v_cndmask_b32_e32 v97, 0, v79, vcc
	v_cmp_lt_i32_e32 vcc, v100, v35
	s_nop 1
	v_cndmask_b32_e32 v96, 0, v78, vcc
	v_pk_add_f32 v[78:79], v[94:95], v[96:97]
	v_cmp_ge_i32_e32 vcc, s56, v70
	v_or_b32_e32 v70, 56, v50
	v_mov_b32_dpp v80, v78 quad_perm:[1,0,3,2] row_mask:0xf bank_mask:0xf
	v_mov_b32_dpp v81, v79 quad_perm:[1,0,3,2] row_mask:0xf bank_mask:0xf
	v_pk_add_f32 v[78:79], v[78:79], v[80:81]
	v_mov_b32_e32 v80, v17
	v_mov_b32_e32 v81, v17
	s_nop 0
	v_mov_b32_dpp v80, v78 quad_perm:[2,3,0,1] row_mask:0xf bank_mask:0xf
	v_mov_b32_dpp v81, v79 quad_perm:[2,3,0,1] row_mask:0xf bank_mask:0xf
	v_pk_add_f32 v[78:79], v[78:79], v[80:81]
	s_nop 0
	v_and_b32_e32 v73, 0xffffff80, v79
	v_and_b32_e32 v75, 0xffffff80, v78
	v_or_b32_e32 v73, v73, v50
	v_or_b32_e32 v75, v75, v50
	v_xor_b32_e32 v77, 0x4e, v73
	v_xor_b32_e32 v73, 0x4f, v75
	v_cndmask_b32_e32 v73, 0, v73, vcc
	v_cmp_ge_i32_e32 vcc, s56, v54
	v_pk_mul_f32 v[78:79], v[36:37], v[82:83] op_sel_hi:[0,1]
	v_or_b32_e32 v54, 57, v50
	v_cndmask_b32_e32 v75, 0, v77, vcc
	v_cmp_lt_i32_e32 vcc, v101, v35
	s_nop 1
	v_cndmask_b32_e32 v99, 0, v79, vcc
	v_cmp_lt_i32_e32 vcc, v102, v35
	s_nop 1
	v_cndmask_b32_e32 v98, 0, v78, vcc
	v_pk_mul_f32 v[78:79], v[36:37], v[90:91] op_sel_hi:[0,1]
	v_cmp_lt_i32_e32 vcc, v103, v35
	s_nop 1
	v_cndmask_b32_e32 v91, 0, v79, vcc
	v_cmp_lt_i32_e32 vcc, v105, v35
	s_nop 1
	v_cndmask_b32_e32 v90, 0, v78, vcc
	v_cvt_pk_bf16_f32 v78, v84, v86
	v_cvt_pk_bf16_f32 v79, v85, v87
	v_cvt_pk_bf16_f32 v80, v92, v88
	v_cvt_pk_bf16_f32 v81, v93, v89
	v_cvt_pk_bf16_f32 v82, v94, v96
	v_cvt_pk_bf16_f32 v83, v95, v97
	v_cvt_pk_bf16_f32 v84, v98, v90
	v_cvt_pk_bf16_f32 v85, v99, v91
	v_pk_add_f32 v[118:119], v[98:99], v[90:91]
	ds_read_b64_tr_b16 v[88:89], v40 offset:48384
	ds_read_b64_tr_b16 v[90:91], v40 offset:50688
	ds_read_b64_tr_b16 v[92:93], v40 offset:52992
	ds_read_b64_tr_b16 v[86:87], v40 offset:46080
	ds_read_b64_tr_b16 v[94:95], v40 offset:46112
	ds_read_b64_tr_b16 v[98:99], v40 offset:46144
	ds_read_b64_tr_b16 v[102:103], v40 offset:46176
	ds_read_b64_tr_b16 v[96:97], v40 offset:48416
	ds_read_b64_tr_b16 v[100:101], v40 offset:48448
	ds_read_b64_tr_b16 v[104:105], v40 offset:48480
	ds_read_b64_tr_b16 v[106:107], v40 offset:50720
	ds_read_b64_tr_b16 v[110:111], v40 offset:50752
	ds_read_b64_tr_b16 v[114:115], v40 offset:50784
	ds_read_b64_tr_b16 v[108:109], v40 offset:53024
	ds_read_b64_tr_b16 v[112:113], v40 offset:53056
	ds_read_b64_tr_b16 v[116:117], v40 offset:53088
	v_mov_b32_dpp v120, v118 quad_perm:[1,0,3,2] row_mask:0xf bank_mask:0xf
	v_mov_b32_dpp v121, v119 quad_perm:[1,0,3,2] row_mask:0xf bank_mask:0xf
	s_waitcnt lgkmcnt(12)
	v_mfma_f32_16x16x32_bf16 v[26:29], v[86:89], v[78:81], v[26:29]
	v_add_f32_e64 v86, v118, v120
	v_add_f32_e64 v87, v119, v121
	v_mov_b32_e32 v88, v17
	v_mov_b32_e32 v89, v17
	s_waitcnt lgkmcnt(8)
	v_mfma_f32_16x16x32_bf16 v[8:11], v[94:97], v[78:81], v[8:11]
	v_mov_b32_dpp v88, v86 quad_perm:[2,3,0,1] row_mask:0xf bank_mask:0xf
	v_mov_b32_dpp v89, v87 quad_perm:[2,3,0,1] row_mask:0xf bank_mask:0xf
	v_pk_add_f32 v[86:87], v[86:87], v[88:89]
	s_waitcnt lgkmcnt(7)
	v_mfma_f32_16x16x32_bf16 v[12:15], v[98:101], v[78:81], v[12:15]
	v_and_b32_e32 v86, 0xffffff80, v86
	v_and_b32_e32 v77, 0xffffff80, v87
	v_or_b32_e32 v86, v86, v50
	s_waitcnt lgkmcnt(6)
	v_mfma_f32_16x16x32_bf16 v[22:25], v[102:105], v[78:81], v[22:25]
	v_or_b32_e32 v77, v77, v50
	v_xor_b32_e32 v86, 0x47, v86
	v_cmp_ge_i32_e32 vcc, s56, v70
	v_mfma_f32_16x16x32_bf16 v[26:29], v[90:93], v[82:85], v[26:29]
	v_xor_b32_e32 v77, 0x46, v77
	v_cndmask_b32_e32 v78, 0, v86, vcc
	v_cmp_ge_i32_e32 vcc, s56, v54
	s_waitcnt lgkmcnt(2)
	v_mfma_f32_16x16x32_bf16 v[8:11], v[106:109], v[82:85], v[8:11]
	v_cndmask_b32_e32 v54, 0, v77, vcc
	s_waitcnt lgkmcnt(1)
	v_mfma_f32_16x16x32_bf16 v[12:15], v[110:113], v[82:85], v[12:15]
	s_waitcnt lgkmcnt(0)
	v_mfma_f32_16x16x32_bf16 v[22:25], v[114:117], v[82:85], v[22:25]
	s_branch .LBB0_1031

.LBB0_1266:
	v_mov_b32_e32 v74, v200
	s_nop 1
	v_permlane16_swap_b32_e32 v200, v74
	v_max_f32_e32 v74, v74, v74
	v_max_f32_e32 v75, v200, v200
	v_max_f32_e32 v74, v75, v74
	v_mov_b32_e32 v75, v74
	s_nop 1
	v_permlane32_swap_b32_e32 v74, v75
	v_max3_f32 v122, v192, v74, v75
	v_max_f32_e32 v75, 0xe0ad78ec, v122
	v_mov_b32_e32 v74, v15
	v_pk_mul_f32 v[74:75], v[74:75], s[70:71] op_sel_hi:[1,0]
	s_nop 0
	v_pk_fma_f32 v[0:1], v[0:1], s[70:71], v[74:75] op_sel:[0,0,1] op_sel_hi:[1,0,1] neg_lo:[0,0,1] neg_hi:[0,0,1]
	v_exp_f32_e32 v15, v0
	v_exp_f32_e32 v1, v1
	v_pk_fma_f32 v[2:3], v[2:3], s[70:71], v[74:75] op_sel:[0,0,1] op_sel_hi:[1,0,1] neg_lo:[0,0,1] neg_hi:[0,0,1]
	v_exp_f32_e32 v2, v2
	v_exp_f32_e32 v3, v3
	v_pk_fma_f32 v[4:5], v[4:5], s[70:71], v[74:75] op_sel:[0,0,1] op_sel_hi:[1,0,1] neg_lo:[0,0,1] neg_hi:[0,0,1]
	v_add_f32_e32 v76, 0, v15
	v_exp_f32_e32 v4, v4
	v_add_f32_e32 v76, v1, v76
	v_exp_f32_e32 v5, v5
	v_pk_fma_f32 v[6:7], v[6:7], s[70:71], v[74:75] op_sel:[0,0,1] op_sel_hi:[1,0,1] neg_lo:[0,0,1] neg_hi:[0,0,1]
	v_add_f32_e32 v76, v2, v76
	v_exp_f32_e32 v6, v6
	v_add_f32_e32 v76, v3, v76
	v_exp_f32_e32 v7, v7
	v_pk_fma_f32 v[8:9], v[8:9], s[70:71], v[74:75] op_sel:[0,0,1] op_sel_hi:[1,0,1] neg_lo:[0,0,1] neg_hi:[0,0,1]
	v_add_f32_e32 v76, v4, v76
	v_exp_f32_e32 v8, v8
	v_add_f32_e32 v76, v5, v76
	v_exp_f32_e32 v9, v9
	v_pk_fma_f32 v[10:11], v[10:11], s[70:71], v[74:75] op_sel:[0,0,1] op_sel_hi:[1,0,1] neg_lo:[0,0,1] neg_hi:[0,0,1]
	v_add_f32_e32 v76, v6, v76
	v_exp_f32_e32 v10, v10
	v_add_f32_e32 v76, v7, v76
	v_exp_f32_e32 v11, v11
	v_pk_fma_f32 v[12:13], v[12:13], s[70:71], v[74:75] op_sel:[0,0,1] op_sel_hi:[1,0,1] neg_lo:[0,0,1] neg_hi:[0,0,1]
	v_add_f32_e32 v76, v8, v76
	v_exp_f32_e32 v12, v12
	v_add_f32_e32 v76, v9, v76
	v_exp_f32_e32 v13, v13
	v_fma_f32 v14, v14, s70, -v75
	v_sub_f32_e32 v0, v192, v122
	v_add_f32_e32 v76, v10, v76
	v_exp_f32_e32 v14, v14
	v_sub_f32_e32 v74, v74, v75
	v_mul_f32_e32 v0, 0x3e38aa3b, v0
	v_add_f32_e32 v76, v11, v76
	v_exp_f32_e32 v85, v74
	v_add_f32_e32 v76, v12, v76
	v_exp_f32_e32 v0, v0
	v_add_f32_e32 v74, v13, v76
	v_add_f32_e32 v74, v14, v74
	v_add_f32_e32 v123, v85, v74
	v_fmac_f32_e32 v123, v133, v0
	v_pk_mul_f32 v[72:73], v[72:73], v[0:1] op_sel_hi:[1,0]
	v_pk_mul_f32 v[70:71], v[70:71], v[0:1] op_sel_hi:[1,0]
	v_pk_mul_f32 v[64:65], v[64:65], v[0:1] op_sel_hi:[1,0]
	v_pk_mul_f32 v[62:63], v[62:63], v[0:1] op_sel_hi:[1,0]
	v_pk_mul_f32 v[56:57], v[56:57], v[0:1] op_sel_hi:[1,0]
	v_pk_mul_f32 v[54:55], v[54:55], v[0:1] op_sel_hi:[1,0]
	v_pk_mul_f32 v[48:49], v[48:49], v[0:1] op_sel_hi:[1,0]
	v_pk_mul_f32 v[46:47], v[46:47], v[0:1] op_sel_hi:[1,0]
	v_mov_b32_e32 v192, v122
	v_mov_b32_e32 v133, v123
	v_cvt_pk_bf16_f32 v74, v15, v1
	v_cvt_pk_bf16_f32 v75, v2, v3
	v_cvt_pk_bf16_f32 v76, v4, v5
	v_cvt_pk_bf16_f32 v77, v6, v7
	v_cvt_pk_bf16_f32 v82, v8, v9
	v_cvt_pk_bf16_f32 v83, v10, v11
	v_cvt_pk_bf16_f32 v84, v12, v13
	v_cvt_pk_bf16_f32 v85, v14, v85

.LBB0_1271:
	v_mov_b32_e32 v78, v95
	s_nop 1
	v_permlane16_swap_b32_e32 v95, v78
	v_max_f32_e32 v78, v78, v78
	v_max_f32_e32 v79, v95, v95
	v_max_f32_e32 v78, v79, v78
	v_mov_b32_e32 v79, v78
	s_nop 1
	v_permlane32_swap_b32_e32 v78, v79
	v_max3_f32 v90, v191, v78, v79
	v_max_f32_e32 v79, 0xe0ad78ec, v90
	v_mov_b32_e32 v78, v15
	v_pk_mul_f32 v[78:79], v[78:79], s[70:71] op_sel_hi:[1,0]
	s_nop 0
	v_pk_fma_f32 v[0:1], v[0:1], s[70:71], v[78:79] op_sel:[0,0,1] op_sel_hi:[1,0,1] neg_lo:[0,0,1] neg_hi:[0,0,1]
	v_exp_f32_e32 v15, v0
	v_exp_f32_e32 v1, v1
	v_pk_fma_f32 v[2:3], v[2:3], s[70:71], v[78:79] op_sel:[0,0,1] op_sel_hi:[1,0,1] neg_lo:[0,0,1] neg_hi:[0,0,1]
	v_exp_f32_e32 v2, v2
	v_exp_f32_e32 v3, v3
	v_pk_fma_f32 v[4:5], v[4:5], s[70:71], v[78:79] op_sel:[0,0,1] op_sel_hi:[1,0,1] neg_lo:[0,0,1] neg_hi:[0,0,1]
	v_add_f32_e32 v80, 0, v15
	v_exp_f32_e32 v4, v4
	v_add_f32_e32 v80, v1, v80
	v_exp_f32_e32 v5, v5
	v_pk_fma_f32 v[6:7], v[6:7], s[70:71], v[78:79] op_sel:[0,0,1] op_sel_hi:[1,0,1] neg_lo:[0,0,1] neg_hi:[0,0,1]
	v_add_f32_e32 v80, v2, v80
	v_exp_f32_e32 v6, v6
	v_add_f32_e32 v80, v3, v80
	v_exp_f32_e32 v7, v7
	v_pk_fma_f32 v[8:9], v[8:9], s[70:71], v[78:79] op_sel:[0,0,1] op_sel_hi:[1,0,1] neg_lo:[0,0,1] neg_hi:[0,0,1]
	v_add_f32_e32 v80, v4, v80
	v_exp_f32_e32 v8, v8
	v_add_f32_e32 v80, v5, v80
	v_exp_f32_e32 v9, v9
	v_pk_fma_f32 v[10:11], v[10:11], s[70:71], v[78:79] op_sel:[0,0,1] op_sel_hi:[1,0,1] neg_lo:[0,0,1] neg_hi:[0,0,1]
	v_add_f32_e32 v80, v6, v80
	v_exp_f32_e32 v10, v10
	v_add_f32_e32 v80, v7, v80
	v_exp_f32_e32 v11, v11
	v_pk_fma_f32 v[12:13], v[12:13], s[70:71], v[78:79] op_sel:[0,0,1] op_sel_hi:[1,0,1] neg_lo:[0,0,1] neg_hi:[0,0,1]
	v_add_f32_e32 v80, v8, v80
	v_exp_f32_e32 v12, v12
	v_add_f32_e32 v80, v9, v80
	v_exp_f32_e32 v13, v13
	v_fma_f32 v14, v14, s70, -v79
	v_sub_f32_e32 v0, v191, v90
	v_add_f32_e32 v80, v10, v80
	v_exp_f32_e32 v14, v14
	v_sub_f32_e32 v78, v78, v79
	v_mul_f32_e32 v0, 0x3e38aa3b, v0
	v_add_f32_e32 v80, v11, v80
	v_exp_f32_e32 v89, v78
	v_add_f32_e32 v80, v12, v80
	v_exp_f32_e32 v0, v0
	v_add_f32_e32 v78, v13, v80
	v_add_f32_e32 v78, v14, v78
	v_add_f32_e32 v91, v89, v78
	v_fmac_f32_e32 v91, v152, v0
	v_pk_mul_f32 v[68:69], v[68:69], v[0:1] op_sel_hi:[1,0]
	v_pk_mul_f32 v[66:67], v[66:67], v[0:1] op_sel_hi:[1,0]
	v_pk_mul_f32 v[60:61], v[60:61], v[0:1] op_sel_hi:[1,0]
	v_pk_mul_f32 v[58:59], v[58:59], v[0:1] op_sel_hi:[1,0]
	v_pk_mul_f32 v[52:53], v[52:53], v[0:1] op_sel_hi:[1,0]
	v_pk_mul_f32 v[50:51], v[50:51], v[0:1] op_sel_hi:[1,0]
	v_pk_mul_f32 v[44:45], v[44:45], v[0:1] op_sel_hi:[1,0]
	v_pk_mul_f32 v[42:43], v[42:43], v[0:1] op_sel_hi:[1,0]
	v_mov_b32_e32 v191, v90
	v_mov_b32_e32 v152, v91
	v_cvt_pk_bf16_f32 v78, v15, v1
	v_cvt_pk_bf16_f32 v79, v2, v3
	v_cvt_pk_bf16_f32 v80, v4, v5
	v_cvt_pk_bf16_f32 v81, v6, v7
	v_cvt_pk_bf16_f32 v86, v8, v9
	v_cvt_pk_bf16_f32 v87, v10, v11
	v_cvt_pk_bf16_f32 v88, v12, v13
	v_cvt_pk_bf16_f32 v89, v14, v89

.LBB0_1416:
	v_add_f32_e32 v75, 0, v107
	v_add_f32_e32 v75, v108, v75
	v_add_f32_e32 v75, v109, v75
	v_add_f32_e32 v75, v110, v75
	v_add_f32_e32 v75, v111, v75
	v_add_f32_e32 v75, v112, v75
	v_add_f32_e32 v75, v113, v75
	v_add_f32_e32 v75, v151, v75
	v_add_f32_e32 v75, v152, v75
	v_add_f32_e32 v75, v170, v75
	v_sub_f32_e32 v74, v127, v106
	v_add_f32_e32 v75, v174, v75
	v_mul_f32_e32 v74, 0x3e38aa3b, v74
	v_add_f32_e32 v75, v175, v75
	v_add_f32_e32 v75, v176, v75
	v_exp_f32_e32 v74, v74
	v_add_f32_e32 v75, v177, v75
	v_add_f32_e32 v75, v182, v75
	v_add_f32_e32 v83, v183, v75
	v_fmac_f32_e32 v83, v119, v74
	v_pk_mul_f32 v[64:65], v[64:65], v[74:75] op_sel_hi:[1,0]
	v_pk_mul_f32 v[62:63], v[62:63], v[74:75] op_sel_hi:[1,0]
	v_pk_mul_f32 v[60:61], v[60:61], v[74:75] op_sel_hi:[1,0]
	v_pk_mul_f32 v[58:59], v[58:59], v[74:75] op_sel_hi:[1,0]
	v_pk_mul_f32 v[56:57], v[56:57], v[74:75] op_sel_hi:[1,0]
	v_pk_mul_f32 v[54:55], v[54:55], v[74:75] op_sel_hi:[1,0]
	v_pk_mul_f32 v[52:53], v[52:53], v[74:75] op_sel_hi:[1,0]
	v_pk_mul_f32 v[50:51], v[50:51], v[74:75] op_sel_hi:[1,0]
	v_mov_b32_e32 v74, v78
	s_nop 1
	v_permlane16_swap_b32_e32 v78, v74
	v_max_f32_e32 v74, v74, v74
	v_max_f32_e32 v75, v78, v78
	v_max_f32_e32 v74, v75, v74
	v_mov_b32_e32 v75, v74
	s_nop 1
	v_permlane32_swap_b32_e32 v74, v75
	v_max3_f32 v84, v126, v74, v75
	v_sub_f32_e32 v74, v126, v84
	v_mul_f32_e32 v76, 0x3e38aa3b, v74
	v_max_f32_e32 v75, 0xe0ad78ec, v84
	v_mov_b32_e32 v74, v14
	v_pk_mul_f32 v[74:75], v[74:75], s[70:71] op_sel_hi:[1,0]
	v_mov_b32_e32 v126, v84
	v_pk_fma_f32 v[0:1], v[0:1], s[70:71], v[74:75] op_sel:[0,0,1] op_sel_hi:[1,0,1] neg_lo:[0,0,1] neg_hi:[0,0,1]
	v_exp_f32_e32 v14, v0
	v_exp_f32_e32 v77, v1
	v_fma_f32 v1, v2, s70, -v75
	v_exp_f32_e32 v78, v1
	v_fma_f32 v1, v3, s70, -v75
	v_exp_f32_e32 v79, v1
	v_fma_f32 v1, v4, s70, -v75
	v_add_f32_e32 v0, 0, v14
	v_exp_f32_e32 v80, v1
	v_fma_f32 v1, v5, s70, -v75
	v_add_f32_e32 v0, v77, v0
	v_exp_f32_e32 v81, v1
	v_fma_f32 v1, v6, s70, -v75
	v_add_f32_e32 v0, v78, v0
	v_exp_f32_e32 v85, v1
	v_fma_f32 v1, v7, s70, -v75
	v_add_f32_e32 v0, v79, v0
	v_exp_f32_e32 v86, v1
	v_fma_f32 v1, v8, s70, -v75
	v_add_f32_e32 v0, v80, v0
	v_exp_f32_e32 v87, v1
	v_fma_f32 v1, v9, s70, -v75
	v_add_f32_e32 v0, v81, v0
	v_exp_f32_e32 v88, v1
	v_fma_f32 v1, v10, s70, -v75
	v_add_f32_e32 v0, v85, v0
	v_exp_f32_e32 v89, v1
	v_fma_f32 v1, v11, s70, -v75
	v_add_f32_e32 v0, v86, v0
	v_exp_f32_e32 v90, v1
	v_fma_f32 v1, v12, s70, -v75
	v_add_f32_e32 v0, v87, v0
	v_exp_f32_e32 v91, v1
	v_fma_f32 v1, v13, s70, -v75
	v_add_f32_e32 v0, v88, v0
	v_exp_f32_e32 v92, v1
	v_sub_f32_e32 v1, v74, v75
	v_add_f32_e32 v0, v89, v0
	v_exp_f32_e32 v74, v1
	v_fma_f32 v1, v15, s70, -v75
	v_add_f32_e32 v0, v90, v0
	v_exp_f32_e32 v15, v1
	v_add_f32_e32 v0, v91, v0
	v_add_f32_e32 v0, v92, v0
	v_add_f32_e32 v0, v74, v0
	v_add_f32_e32 v82, v15, v0
	v_exp_f32_e32 v0, v76
	v_add_u32_e32 v76, s13, v128
	v_fmac_f32_e32 v82, v118, v0
	v_pk_mul_f32 v[48:49], v[48:49], v[0:1] op_sel_hi:[1,0]
	v_pk_mul_f32 v[46:47], v[46:47], v[0:1] op_sel_hi:[1,0]
	v_pk_mul_f32 v[10:11], v[44:45], v[0:1] op_sel_hi:[1,0]
	v_pk_mul_f32 v[8:9], v[42:43], v[0:1] op_sel_hi:[1,0]
	v_pk_mul_f32 v[6:7], v[40:41], v[0:1] op_sel_hi:[1,0]
	v_pk_mul_f32 v[4:5], v[38:39], v[0:1] op_sel_hi:[1,0]
	v_pk_mul_f32 v[2:3], v[20:21], v[0:1] op_sel_hi:[1,0]
	v_pk_mul_f32 v[0:1], v[18:19], v[0:1] op_sel_hi:[1,0]
	v_cvt_pk_bf16_f32 v18, v14, v77
	v_cvt_pk_bf16_f32 v19, v78, v79
	v_cvt_pk_bf16_f32 v20, v80, v81
	v_cvt_pk_bf16_f32 v21, v85, v86
	v_cvt_pk_bf16_f32 v12, v87, v88
	v_cvt_pk_bf16_f32 v13, v89, v90
	v_cvt_pk_bf16_f32 v14, v91, v92
	v_cvt_pk_bf16_f32 v15, v74, v15
	v_add_u32_e32 v44, s13, v148
	v_add_u32_e32 v74, s13, v133
	s_waitcnt vmcnt(0)
	ds_read_b64_tr_b16 v[38:39], v44 offset:8192
	ds_read_b64_tr_b16 v[40:41], v44 offset:10240
	ds_read_b64_tr_b16 v[42:43], v44 offset:12288
	ds_read_b64_tr_b16 v[44:45], v44 offset:14336
	ds_read_b64_tr_b16 v[86:87], v74 offset:8192
	ds_read_b64_tr_b16 v[88:89], v74 offset:10240
	ds_read_b64_tr_b16 v[90:91], v74 offset:12288
	ds_read_b64_tr_b16 v[92:93], v74 offset:14336
	v_add_u32_e32 v74, s13, v129
	ds_read_b64_tr_b16 v[94:95], v74 offset:8192
	ds_read_b64_tr_b16 v[96:97], v74 offset:10240
	ds_read_b64_tr_b16 v[98:99], v74 offset:12288
	ds_read_b64_tr_b16 v[100:101], v74 offset:14336
	ds_read_b64_tr_b16 v[78:79], v76 offset:8192
	ds_read_b64_tr_b16 v[80:81], v76 offset:10240
	ds_read_b64_tr_b16 v[74:75], v76 offset:12288
	ds_read_b64_tr_b16 v[76:77], v76 offset:14336
	s_waitcnt lgkmcnt(14)
	v_mfma_f32_16x16x32_bf16 v[62:65], v[38:41], v[70:73], v[62:65]
	v_mov_b64_e32 v[118:119], v[82:83]
	s_waitcnt lgkmcnt(10)
	v_mfma_f32_16x16x32_bf16 v[58:61], v[86:89], v[70:73], v[58:61]
	s_waitcnt lgkmcnt(6)
	v_mfma_f32_16x16x32_bf16 v[54:57], v[94:97], v[70:73], v[54:57]
	s_waitcnt lgkmcnt(2)
	v_mfma_f32_16x16x32_bf16 v[50:53], v[78:81], v[70:73], v[50:53]
	v_mfma_f32_16x16x32_bf16 v[38:41], v[38:41], v[18:21], v[46:49]
	v_mfma_f32_16x16x32_bf16 v[8:11], v[86:89], v[18:21], v[8:11]
	v_mfma_f32_16x16x32_bf16 v[4:7], v[94:97], v[18:21], v[4:7]
	v_mfma_f32_16x16x32_bf16 v[0:3], v[78:81], v[18:21], v[0:3]
	v_mfma_f32_16x16x32_bf16 v[62:65], v[42:45], v[66:69], v[62:65]
	v_mfma_f32_16x16x32_bf16 v[58:61], v[90:93], v[66:69], v[58:61]
	v_mfma_f32_16x16x32_bf16 v[54:57], v[98:101], v[66:69], v[54:57]
	s_waitcnt lgkmcnt(0)
	v_mfma_f32_16x16x32_bf16 v[50:53], v[74:77], v[66:69], v[50:53]
	v_mfma_f32_16x16x32_bf16 v[46:49], v[42:45], v[12:15], v[38:41]
	v_mfma_f32_16x16x32_bf16 v[42:45], v[90:93], v[12:15], v[8:11]
	v_mfma_f32_16x16x32_bf16 v[38:41], v[98:101], v[12:15], v[4:7]
	v_mfma_f32_16x16x32_bf16 v[18:21], v[74:77], v[12:15], v[0:3]
	s_branch .LBB0_1418

.LBB0_1431:
	s_or_b64 exec, exec, s[6:7]
	v_mov_b32_e32 v0, s80
	s_waitcnt lgkmcnt(0)
	s_barrier
	ds_read_b32 v0, v0
	s_mov_b64 s[6:7], -1
	s_waitcnt lgkmcnt(0)
	s_barrier
	v_readfirstlane_b32 s8, v0
	s_cmpk_gt_i32 s8, 0xff
	s_cbranch_scc1 .LBB0_1426
	s_ashr_i32 s6, s8, 31
	s_lshr_b32 s6, s6, 24
	s_add_i32 s6, s8, s6
	s_and_b32 s6, s6, 0xffffff00
	s_sub_i32 s6, s8, s6
	s_ashr_i32 s52, s6, 1
	s_lshl_b32 s20, s52, 2
	s_and_b32 s26, s6, 1
	s_ashr_i32 s53, s52, 31
	s_ashr_i32 s21, s20, 31
	v_mov_b32_e32 v167, v156
	v_readlane_b32 s6, v255, 34
	s_add_u32 s10, s20, 0x4000
	s_addc_u32 s11, s21, 0
	v_add_u32_e32 v0, s6, v167
	v_readlane_b32 s6, v255, 28
	v_readlane_b32 s7, v255, 29
	s_add_u32 s64, s6, s52
	s_addc_u32 s65, s7, s53
	s_lshl_b64 s[6:7], s[64:65], 14
	s_lshl_b32 s8, s26, 13
	v_ashrrev_i32_e32 v8, 3, v0
	s_or_b32 s6, s6, s8
	s_add_u32 s8, s94, s6
	v_ashrrev_i32_e32 v9, 31, v8
	s_addc_u32 s9, s95, s7
	v_lshlrev_b64 v[0:1], 7, v[8:9]
	v_lshl_add_u64 v[2:3], s[8:9], 0, v[0:1]
	v_readlane_b32 s8, v255, 41
	s_add_u32 s6, s8, s6
	s_load_dwordx2 s[24:25], s[0:1], 24
	s_waitcnt lgkmcnt(0)
	v_lshlrev_b32_e32 v4, 4, v167
	s_addc_u32 s7, s50, s7
	s_load_dwordx2 s[22:23], s[0:1], 40
	s_waitcnt lgkmcnt(0)
	v_and_b32_e32 v16, 0x70, v4
	v_lshl_add_u64 v[0:1], s[6:7], 0, v[0:1]
	s_load_dwordx2 s[54:55], s[0:1], 32
	s_waitcnt lgkmcnt(0)
	v_lshl_add_u64 v[2:3], v[2:3], 0, v[16:17]
	v_lshl_add_u64 v[4:5], v[0:1], 0, v[16:17]
	global_load_dwordx4 v[0:3], v[2:3], off
	s_nop 0
	global_load_dwordx4 v[4:7], v[4:5], off
	v_bfe_u32 v173, v167, 2, 2
	s_movk_i32 s6, 0x90
	v_and_b32_e32 v12, 3, v167
	v_mul_lo_u32 v8, v8, s6
	v_or_b32_e32 v158, s10, v173
	v_mov_b32_e32 v159, s11
	v_ashrrev_i32_e32 v172, 4, v167
	v_add3_u32 v10, s97, v8, v16
	v_lshl_or_b32 v161, s26, 2, v12
	v_lshlrev_b64 v[8:9], 10, v[158:159]
	v_lshlrev_b32_e32 v162, 3, v172
	v_lshl_add_u64 v[8:9], s[88:89], 0, v[8:9]
	v_lshlrev_b32_e32 v16, 7, v161
	v_ashrrev_i32_e32 v163, 31, v162
	v_lshl_add_u64 v[8:9], v[8:9], 0, v[16:17]
	v_lshl_add_u64 v[8:9], v[162:163], 1, v[8:9]
	v_and_b32_e32 v174, 15, v167
	v_lshlrev_b32_e32 v160, 2, v172
	v_or_b32_e32 v176, 1, v160
	v_or_b32_e32 v177, 2, v160
	v_or_b32_e32 v182, 3, v160
	v_cmp_gt_i32_e64 s[10:11], 16, v172
	v_cmp_gt_i32_e64 s[12:13], 64, v176
	v_cmp_gt_i32_e64 s[14:15], 64, v177
	v_cmp_gt_i32_e64 s[16:17], 64, v182
	v_cmp_gt_i32_e64 s[18:19], 12, v172
	v_cmp_gt_i32_e64 s[8:9], 8, v172
	v_lshlrev_b32_e32 v175, 3, v167
	s_waitcnt vmcnt(1)
	ds_write_b128 v10, v[0:3]
	s_waitcnt vmcnt(0)
	ds_write_b128 v10, v[4:7] offset:9216
	s_waitcnt lgkmcnt(0)
	s_barrier
	global_load_dwordx4 v[0:3], v[8:9], off
	global_load_dwordx4 v[18:21], v[8:9], off offset:64
	v_and_b32_e32 v4, -16, v167
	v_mul_u32_u24_e32 v5, 0x90, v174
	v_add3_u32 v13, s97, v4, v5
	ds_read_b128 v[4:7], v13
	ds_read_b128 v[8:11], v13 offset:64
	ds_read_b128 v[22:25], v13 offset:2304
	ds_read_b128 v[26:29], v13 offset:2368
	ds_read_b128 v[30:33], v13 offset:4608
	ds_read_b128 v[34:37], v13 offset:4672
	ds_read_b128 v[38:41], v13 offset:6912
	ds_read_b128 v[42:45], v13 offset:6976
	s_waitcnt vmcnt(1) lgkmcnt(7)
	v_mfma_f32_16x16x32_bf16 v[4:7], v[4:7], v[0:3], 0
	s_waitcnt lgkmcnt(5)
	v_mfma_f32_16x16x32_bf16 v[22:25], v[22:25], v[0:3], 0
	s_waitcnt lgkmcnt(3)
	v_mfma_f32_16x16x32_bf16 v[30:33], v[30:33], v[0:3], 0
	s_waitcnt lgkmcnt(1)
	v_mfma_f32_16x16x32_bf16 v[0:3], v[38:41], v[0:3], 0
	s_waitcnt vmcnt(0)
	v_mfma_f32_16x16x32_bf16 v[38:41], v[8:11], v[18:21], v[4:7]
	v_and_b32_e32 v9, 24, v175
	v_lshlrev_b32_e32 v8, 6, v161
	v_lshlrev_b64 v[10:11], 9, v[158:159]
	v_mfma_f32_16x16x32_bf16 v[22:25], v[26:29], v[18:21], v[22:25]
	v_or_b32_e32 v4, v160, v173
	v_mul_lo_u32 v183, v4, s6
	s_nop 1
	v_cndmask_b32_e64 v13, v246, v38, s[10:11]
	v_mfma_f32_16x16x32_bf16 v[4:7], v[34:37], v[18:21], v[30:33]
	v_cmp_gt_i32_e64 s[6:7], 4, v172
	s_nop 0
	v_cndmask_b32_e64 v26, v246, v23, s[18:19]
	v_cndmask_b32_e64 v27, v246, v24, s[18:19]
	s_waitcnt lgkmcnt(0)
	v_mfma_f32_16x16x32_bf16 v[0:3], v[42:45], v[18:21], v[0:3]
	v_cndmask_b32_e64 v18, v246, v39, s[12:13]
	v_cndmask_b32_e64 v19, v246, v40, s[14:15]
	v_cndmask_b32_e64 v20, v246, v41, s[16:17]
	v_max3_f32 v15, v13, s96, v18
	v_cndmask_b32_e64 v21, v246, v22, s[18:19]
	v_max3_f32 v15, v15, v19, v20
	v_cndmask_b32_e64 v28, v246, v25, s[18:19]
	v_max3_f32 v15, v15, v21, v26
	v_cndmask_b32_e64 v29, v246, v4, s[8:9]
	v_cndmask_b32_e64 v30, v246, v5, s[8:9]
	v_max3_f32 v15, v15, v27, v28
	v_cndmask_b32_e64 v31, v246, v6, s[8:9]
	v_cndmask_b32_e64 v32, v246, v7, s[8:9]
	v_max3_f32 v15, v15, v29, v30
	v_cndmask_b32_e64 v33, v246, v0, s[6:7]
	v_cndmask_b32_e64 v34, v246, v1, s[6:7]
	v_max3_f32 v15, v15, v31, v32
	v_cndmask_b32_e64 v35, v246, v2, s[6:7]
	v_cndmask_b32_e64 v36, v246, v3, s[6:7]
	v_max3_f32 v15, v15, v33, v34
	v_max3_f32 v15, v15, v35, v36
	v_mov_b32_e32 v37, v15
	s_nop 1
	v_permlane16_swap_b32_e32 v15, v37
	v_max_f32_e32 v37, v37, v37
	v_max_f32_e32 v15, v15, v15
	v_max_f32_e32 v15, v15, v37
	v_mov_b32_e32 v37, v15
	s_nop 1
	v_permlane32_swap_b32_e32 v15, v37
	v_max_f32_e32 v37, v37, v37
	v_max_f32_e32 v15, v15, v15
	v_max_f32_e32 v37, v15, v37
	v_mov_b32_e32 v14, v38
	v_max_f32_e32 v15, 0xe0ad78ec, v37
	v_pk_mul_f32 v[14:15], v[14:15], s[70:71] op_sel_hi:[1,0]
	v_max_f32_e32 v37, 0xf149f2ca, v37
	v_fma_f32 v13, v13, s70, -v15
	v_pk_fma_f32 v[18:19], v[18:19], s[70:71], v[14:15] op_sel:[0,0,1] op_sel_hi:[1,0,1] neg_lo:[0,0,1] neg_hi:[0,0,1]
	v_exp_f32_e32 v13, v13
	v_exp_f32_e32 v18, v18
	v_pk_fma_f32 v[20:21], v[20:21], s[70:71], v[14:15] op_sel:[0,0,1] op_sel_hi:[1,0,1] neg_lo:[0,0,1] neg_hi:[0,0,1]
	v_exp_f32_e32 v19, v19
	v_exp_f32_e32 v20, v20
	v_pk_fma_f32 v[26:27], v[26:27], s[70:71], v[14:15] op_sel:[0,0,1] op_sel_hi:[1,0,1] neg_lo:[0,0,1] neg_hi:[0,0,1]
	v_exp_f32_e32 v21, v21
	v_add_f32_e32 v13, 0, v13
	v_exp_f32_e32 v26, v26
	v_add_f32_e32 v13, v18, v13
	v_pk_fma_f32 v[28:29], v[28:29], s[70:71], v[14:15] op_sel:[0,0,1] op_sel_hi:[1,0,1] neg_lo:[0,0,1] neg_hi:[0,0,1]
	v_exp_f32_e32 v27, v27
	v_add_f32_e32 v13, v19, v13
	v_exp_f32_e32 v28, v28
	v_add_f32_e32 v13, v20, v13
	v_pk_fma_f32 v[30:31], v[30:31], s[70:71], v[14:15] op_sel:[0,0,1] op_sel_hi:[1,0,1] neg_lo:[0,0,1] neg_hi:[0,0,1]
	v_exp_f32_e32 v29, v29
	v_add_f32_e32 v13, v21, v13
	v_exp_f32_e32 v30, v30
	v_add_f32_e32 v13, v26, v13
	v_pk_fma_f32 v[32:33], v[32:33], s[70:71], v[14:15] op_sel:[0,0,1] op_sel_hi:[1,0,1] neg_lo:[0,0,1] neg_hi:[0,0,1]
	v_exp_f32_e32 v31, v31
	v_add_f32_e32 v13, v27, v13
	v_exp_f32_e32 v32, v32
	v_add_f32_e32 v13, v28, v13
	v_pk_fma_f32 v[34:35], v[34:35], s[70:71], v[14:15] op_sel:[0,0,1] op_sel_hi:[1,0,1] neg_lo:[0,0,1] neg_hi:[0,0,1]
	v_exp_f32_e32 v33, v33
	v_add_f32_e32 v13, v29, v13
	v_exp_f32_e32 v34, v34
	v_add_f32_e32 v13, v30, v13
	v_sub_f32_e32 v37, 0xf149f2ca, v37
	v_fma_f32 v36, v36, s70, -v15
	v_exp_f32_e32 v35, v35
	v_add_f32_e32 v13, v31, v13
	v_mul_f32_e32 v37, 0x3e38aa3b, v37
	v_exp_f32_e32 v36, v36
	v_add_f32_e32 v13, v32, v13
	v_exp_f32_e32 v37, v37
	v_add_f32_e32 v13, v33, v13
	v_add_f32_e32 v13, v34, v13
	v_add_f32_e32 v13, v35, v13
	v_add_f32_e32 v13, v36, v13
	v_fmac_f32_e32 v13, 0, v37
	v_mov_b32_e32 v18, v13
	s_nop 1
	v_permlane16_swap_b32_e32 v13, v18
	v_add_f32_e32 v13, v13, v18
	v_mov_b32_e32 v18, v13
	s_nop 1
	v_permlane32_swap_b32_e32 v13, v18
	v_add_f32_e32 v13, v13, v18
	v_max_f32_e32 v13, 0xda24260, v13
	v_div_scale_f32 v18, s[28:29], v13, v13, 1.0
	v_rcp_f32_e32 v19, v18
	v_div_scale_f32 v20, vcc, 1.0, v13, 1.0
	v_pk_fma_f32 v[0:1], v[0:1], s[70:71], v[14:15] op_sel:[0,0,1] op_sel_hi:[1,0,1] neg_lo:[0,0,1] neg_hi:[0,0,1]
	v_fma_f32 v21, -v18, v19, 1.0
	v_fmac_f32_e32 v19, v21, v19
	v_mul_f32_e32 v21, v20, v19
	v_fma_f32 v26, -v18, v21, v20
	v_fmac_f32_e32 v21, v26, v19
	v_exp_f32_e32 v0, v0
	v_fma_f32 v18, -v18, v21, v20
	v_exp_f32_e32 v1, v1
	v_div_fmas_f32 v18, v18, v19, v21
	v_div_fixup_f32 v13, v18, v13, 1.0
	v_mul_f32_e32 v0, v13, v0
	v_sub_f32_e32 v14, v14, v15
	v_fma_f32 v38, v39, s70, -v15
	v_cndmask_b32_e64 v64, 0, v0, s[6:7]
	v_mul_f32_e32 v0, v13, v1
	v_fma_f32 v1, v2, s70, -v15
	v_fma_f32 v39, v40, s70, -v15
	v_fma_f32 v40, v41, s70, -v15
	v_pk_fma_f32 v[22:23], v[22:23], s[70:71], v[14:15] op_sel:[0,0,1] op_sel_hi:[1,0,1] neg_lo:[0,0,1] neg_hi:[0,0,1]
	v_pk_fma_f32 v[24:25], v[24:25], s[70:71], v[14:15] op_sel:[0,0,1] op_sel_hi:[1,0,1] neg_lo:[0,0,1] neg_hi:[0,0,1]
	v_exp_f32_e32 v14, v14
	v_exp_f32_e32 v38, v38
	v_exp_f32_e32 v1, v1
	v_fma_f32 v2, v3, s70, -v15
	v_exp_f32_e32 v39, v39
	v_exp_f32_e32 v40, v40
	v_exp_f32_e32 v22, v22
	v_exp_f32_e32 v23, v23
	v_exp_f32_e32 v24, v24
	v_exp_f32_e32 v25, v25
	v_pk_fma_f32 v[6:7], v[6:7], s[70:71], v[14:15] op_sel:[0,0,1] op_sel_hi:[1,0,1] neg_lo:[0,0,1] neg_hi:[0,0,1]
	v_exp_f32_e32 v2, v2
	v_exp_f32_e32 v6, v6
	v_pk_fma_f32 v[4:5], v[4:5], s[70:71], v[14:15] op_sel:[0,0,1] op_sel_hi:[1,0,1] neg_lo:[0,0,1] neg_hi:[0,0,1]
	v_exp_f32_e32 v7, v7
	v_exp_f32_e32 v4, v4
	v_exp_f32_e32 v5, v5
	v_mul_f32_e32 v14, v13, v14
	v_mul_f32_e32 v18, v13, v38
	v_cndmask_b32_e64 v65, 0, v0, s[6:7]
	v_mul_f32_e32 v0, v13, v1
	v_mul_f32_e32 v19, v13, v39
	v_mul_f32_e32 v20, v13, v40
	v_mul_f32_e32 v21, v13, v22
	v_mul_f32_e32 v22, v13, v23
	v_mul_f32_e32 v23, v13, v24
	v_mul_f32_e32 v24, v13, v25
	v_cndmask_b32_e64 v14, 0, v14, s[10:11]
	v_cndmask_b32_e64 v25, 0, v18, s[12:13]
	v_cndmask_b32_e64 v66, 0, v0, s[6:7]
	v_mul_f32_e32 v0, v13, v2
	v_cndmask_b32_e64 v26, 0, v19, s[14:15]
	v_cndmask_b32_e64 v27, 0, v20, s[16:17]
	v_mul_f32_e32 v6, v13, v6
	v_cndmask_b32_e64 v67, 0, v0, s[6:7]
	v_add_f32_e32 v0, v14, v25
	v_cndmask_b32_e64 v28, 0, v21, s[18:19]
	v_cndmask_b32_e64 v22, 0, v22, s[18:19]
	v_cndmask_b32_e64 v37, 0, v6, s[8:9]
	v_mul_f32_e32 v6, v13, v7
	v_add_f32_dpp v18, v0, v0 quad_perm:[1,0,3,2] row_mask:0xf bank_mask:0xf bound_ctrl:1
	v_add_f32_e32 v0, v26, v27
	v_mul_f32_e32 v4, v13, v4
	v_cndmask_b32_e64 v23, 0, v23, s[18:19]
	v_cndmask_b32_e64 v24, 0, v24, s[18:19]
	v_mul_f32_e32 v5, v13, v5
	v_cndmask_b32_e64 v38, 0, v6, s[8:9]
	v_add_f32_dpp v6, v0, v0 quad_perm:[1,0,3,2] row_mask:0xf bank_mask:0xf bound_ctrl:1
	v_add_f32_e32 v0, v28, v22
	v_add3_u32 v16, s97, v9, v183
	v_cndmask_b32_e64 v4, 0, v4, s[8:9]
	v_cndmask_b32_e64 v5, 0, v5, s[8:9]
	v_add_f32_dpp v13, v0, v0 quad_perm:[1,0,3,2] row_mask:0xf bank_mask:0xf bound_ctrl:1
	v_add_f32_e32 v0, v23, v24
	v_cvt_pk_bf16_f32 v20, v14, v25
	v_cvt_pk_bf16_f32 v21, v26, v27
	v_cvt_pk_bf16_f32 v22, v28, v22
	v_cvt_pk_bf16_f32 v23, v23, v24
	v_cvt_pk_bf16_f32 v40, v4, v5
	v_cvt_pk_bf16_f32 v41, v37, v38
	v_cvt_pk_bf16_f32 v42, v64, v65
	v_cvt_pk_bf16_f32 v43, v66, v67
	s_nop 1
	v_add_f32_dpp v36, v0, v0 quad_perm:[1,0,3,2] row_mask:0xf bank_mask:0xf bound_ctrl:1
	ds_read_b64_tr_b16 v[2:3], v16 offset:11520
	ds_read_b64_tr_b16 v[24:25], v16 offset:13824
	ds_read_b64_tr_b16 v[26:27], v16 offset:16128
	ds_read_b64_tr_b16 v[0:1], v16 offset:9216
	ds_read_b64_tr_b16 v[28:29], v16 offset:9248
	ds_read_b64_tr_b16 v[44:45], v16 offset:9280
	ds_read_b64_tr_b16 v[48:49], v16 offset:9312
	ds_read_b64_tr_b16 v[30:31], v16 offset:11552
	ds_read_b64_tr_b16 v[46:47], v16 offset:11584
	ds_read_b64_tr_b16 v[50:51], v16 offset:11616
	ds_read_b64_tr_b16 v[52:53], v16 offset:13856
	ds_read_b64_tr_b16 v[56:57], v16 offset:13888
	ds_read_b64_tr_b16 v[60:61], v16 offset:13920
	s_waitcnt lgkmcnt(9)
	v_mfma_f32_16x16x32_bf16 v[0:3], v[0:3], v[20:23], 0
	ds_read_b64_tr_b16 v[54:55], v16 offset:16160
	ds_read_b64_tr_b16 v[58:59], v16 offset:16192
	ds_read_b64_tr_b16 v[62:63], v16 offset:16224
	v_add_f32_e32 v4, v4, v5
	v_mov_b32_e32 v19, v17
	v_mfma_f32_16x16x32_bf16 v[32:35], v[24:27], v[40:43], v[0:3]
	v_mov_b32_e32 v7, v17
	v_mov_b32_e32 v15, v17
	v_mov_b32_e32 v39, v17
	s_waitcnt lgkmcnt(8)
	v_mfma_f32_16x16x32_bf16 v[0:3], v[28:31], v[20:23], 0
	v_add_f32_dpp v4, v4, v4 quad_perm:[1,0,3,2] row_mask:0xf bank_mask:0xf bound_ctrl:1
	v_mov_b32_e32 v5, v17
	v_mov_b32_e32 v16, v17
	s_waitcnt lgkmcnt(7)
	v_mfma_f32_16x16x32_bf16 v[24:27], v[44:47], v[20:23], 0
	v_mov_b32_dpp v19, v18 quad_perm:[2,3,0,1] row_mask:0xf bank_mask:0xf
	v_mov_b32_dpp v7, v6 quad_perm:[2,3,0,1] row_mask:0xf bank_mask:0xf
	v_mov_b32_dpp v15, v13 quad_perm:[2,3,0,1] row_mask:0xf bank_mask:0xf
	s_waitcnt lgkmcnt(6)
	v_mfma_f32_16x16x32_bf16 v[20:23], v[48:51], v[20:23], 0
	v_mov_b32_dpp v39, v36 quad_perm:[2,3,0,1] row_mask:0xf bank_mask:0xf
	v_mov_b32_dpp v5, v4 quad_perm:[2,3,0,1] row_mask:0xf bank_mask:0xf
	v_cmp_lt_i32_e32 vcc, 1, v12
	s_waitcnt lgkmcnt(2)
	v_mfma_f32_16x16x32_bf16 v[28:31], v[52:55], v[40:43], v[0:3]
	s_nop 2
	v_add_f32_e32 v0, v37, v38
	s_waitcnt lgkmcnt(1)
	v_mfma_f32_16x16x32_bf16 v[24:27], v[56:59], v[40:43], v[24:27]
	v_mov_b32_e32 v3, v17
	v_add_f32_dpp v2, v0, v0 quad_perm:[1,0,3,2] row_mask:0xf bank_mask:0xf bound_ctrl:1
	v_add_f32_e32 v0, v64, v65
	s_waitcnt lgkmcnt(0)
	v_mfma_f32_16x16x32_bf16 v[20:23], v[60:63], v[40:43], v[20:23]
	v_mov_b32_e32 v38, v17
	v_add_f32_dpp v14, v0, v0 quad_perm:[1,0,3,2] row_mask:0xf bank_mask:0xf bound_ctrl:1
	v_add_f32_e32 v0, v66, v67
	v_mov_b32_dpp v3, v2 quad_perm:[2,3,0,1] row_mask:0xf bank_mask:0xf
	v_mov_b32_dpp v16, v14 quad_perm:[2,3,0,1] row_mask:0xf bank_mask:0xf
	v_add_f32_dpp v37, v0, v0 quad_perm:[1,0,3,2] row_mask:0xf bank_mask:0xf bound_ctrl:1
	v_lshlrev_b32_e32 v1, 1, v172
	s_nop 0
	v_mov_b32_dpp v38, v37 quad_perm:[2,3,0,1] row_mask:0xf bank_mask:0xf
	s_and_saveexec_b64 s[6:7], vcc
	s_xor_b64 s[6:7], exec, s[6:7]
	s_cbranch_execz .LBB0_1438
	v_cmp_lt_i32_e32 vcc, 2, v12
	s_and_saveexec_b64 s[8:9], vcc
	s_xor_b64 s[8:9], exec, s[8:9]
	v_add_u32_e32 v0, 8, v1
	v_cmp_gt_u32_e32 vcc, 30, v0
	v_add_f32_e32 v0, v36, v39
	v_and_b32_e32 v0, 0xffffff80, v0
	v_sub_u32_e32 v0, v0, v1
	v_add_u32_e32 v0, 0x76, v0
	v_cndmask_b32_e32 v0, 0, v0, vcc
	s_andn2_saveexec_b64 s[8:9], s[8:9]
	v_add_u32_e32 v0, 7, v1
	v_cmp_gt_u32_e32 vcc, 30, v0
	v_add_f32_e32 v0, v13, v15
	v_and_b32_e32 v0, 0xffffff80, v0
	v_sub_u32_e32 v0, v0, v1
	v_add_u32_e32 v0, 0x77, v0
	v_cndmask_b32_e32 v0, 0, v0, vcc
	s_or_b64 exec, exec, s[8:9]

.LBB0_1458:
	v_mov_b32_e32 v16, v18
	s_nop 1
	v_permlane16_swap_b32_e32 v18, v16
	v_max_f32_e32 v16, v16, v16
	v_max_f32_e32 v18, v18, v18
	v_max_f32_e32 v16, v18, v16
	v_mov_b32_e32 v18, v16
	s_nop 1
	v_permlane32_swap_b32_e32 v16, v18
	v_max3_f32 v16, v168, v16, v18
	v_sub_f32_e32 v18, v168, v16
	v_mul_f32_e32 v60, 0x3e38aa3b, v18
	v_max_f32_e32 v19, 0xe0ad78ec, v16
	v_mov_b32_e32 v18, v15
	v_pk_mul_f32 v[18:19], v[18:19], s[70:71] op_sel_hi:[1,0]
	v_mov_b32_e32 v168, v16
	v_pk_fma_f32 v[0:1], v[0:1], s[70:71], v[18:19] op_sel:[0,0,1] op_sel_hi:[1,0,1] neg_lo:[0,0,1] neg_hi:[0,0,1]
	v_exp_f32_e32 v15, v0
	v_exp_f32_e32 v61, v1
	v_fma_f32 v1, v2, s70, -v19
	v_exp_f32_e32 v62, v1
	v_fma_f32 v1, v3, s70, -v19
	v_exp_f32_e32 v63, v1
	v_fma_f32 v1, v4, s70, -v19
	v_add_f32_e32 v0, 0, v15
	v_exp_f32_e32 v128, v1
	v_fma_f32 v1, v5, s70, -v19
	v_add_f32_e32 v0, v61, v0
	v_exp_f32_e32 v129, v1
	v_fma_f32 v1, v6, s70, -v19
	v_add_f32_e32 v0, v62, v0
	v_exp_f32_e32 v130, v1
	v_fma_f32 v1, v7, s70, -v19
	v_add_f32_e32 v0, v63, v0
	v_exp_f32_e32 v131, v1
	v_fma_f32 v1, v8, s70, -v19
	v_add_f32_e32 v0, v128, v0
	v_exp_f32_e32 v132, v1
	v_fma_f32 v1, v9, s70, -v19
	v_add_f32_e32 v0, v129, v0
	v_exp_f32_e32 v133, v1
	v_fma_f32 v1, v10, s70, -v19
	v_add_f32_e32 v0, v130, v0
	v_exp_f32_e32 v134, v1
	v_fma_f32 v1, v11, s70, -v19
	v_add_f32_e32 v0, v131, v0
	v_exp_f32_e32 v135, v1
	v_fma_f32 v1, v12, s70, -v19
	v_add_f32_e32 v0, v132, v0
	v_exp_f32_e32 v136, v1
	v_fma_f32 v1, v13, s70, -v19
	v_add_f32_e32 v0, v133, v0
	v_exp_f32_e32 v137, v1
	v_fma_f32 v1, v14, s70, -v19
	v_add_f32_e32 v0, v134, v0
	v_exp_f32_e32 v138, v1
	v_sub_f32_e32 v1, v18, v19
	v_add_f32_e32 v0, v135, v0
	v_exp_f32_e32 v18, v1
	v_add_f32_e32 v0, v136, v0
	v_add_f32_e32 v0, v137, v0
	v_add_f32_e32 v0, v138, v0
	v_add_f32_e32 v139, v18, v0
	v_exp_f32_e32 v0, v60
	s_waitcnt vmcnt(8)
	v_cndmask_b32_e64 v19, 0, v66, s[14:15]
	v_fmac_f32_e32 v139, v169, v0
	v_pk_mul_f32 v[46:47], v[46:47], v[0:1] op_sel_hi:[1,0]
	v_pk_mul_f32 v[44:45], v[44:45], v[0:1] op_sel_hi:[1,0]
	v_pk_mul_f32 v[10:11], v[50:51], v[0:1] op_sel_hi:[1,0]
	v_pk_mul_f32 v[8:9], v[48:49], v[0:1] op_sel_hi:[1,0]
	v_pk_mul_f32 v[6:7], v[54:55], v[0:1] op_sel_hi:[1,0]
	v_pk_mul_f32 v[4:5], v[52:53], v[0:1] op_sel_hi:[1,0]
	v_pk_mul_f32 v[2:3], v[58:59], v[0:1] op_sel_hi:[1,0]
	v_pk_mul_f32 v[0:1], v[56:57], v[0:1] op_sel_hi:[1,0]
	v_cvt_pk_bf16_f32 v56, v15, v61
	v_cvt_pk_bf16_f32 v57, v62, v63
	v_cvt_pk_bf16_f32 v58, v128, v129
	v_cvt_pk_bf16_f32 v59, v130, v131
	v_cvt_pk_bf16_f32 v12, v132, v133
	v_cvt_pk_bf16_f32 v13, v134, v135
	v_cvt_pk_bf16_f32 v14, v136, v137
	v_cvt_pk_bf16_f32 v15, v138, v18
	v_cndmask_b32_e64 v48, 0, v67, s[14:15]
	v_cndmask_b32_e64 v18, 0, v64, s[14:15]
	v_cndmask_b32_e64 v49, 0, v65, s[14:15]
	v_cvt_pk_bf16_f32 v18, v18, v49
	v_cvt_pk_bf16_f32 v19, v19, v48
	v_add_u32_e32 v48, v217, v218
	ds_write_b64 v48, v[18:19] offset:18432
	v_cndmask_b32_e64 v19, 0, v74, s[16:17]
	v_cndmask_b32_e64 v48, 0, v75, s[16:17]
	v_cndmask_b32_e64 v18, 0, v72, s[16:17]
	v_cndmask_b32_e64 v49, 0, v73, s[16:17]
	v_cvt_pk_bf16_f32 v18, v18, v49
	v_cvt_pk_bf16_f32 v19, v19, v48
	v_add_u32_e32 v48, v217, v219
	ds_write_b64 v48, v[18:19] offset:18432
	s_waitcnt vmcnt(7)
	v_cndmask_b32_e64 v19, 0, v70, s[18:19]
	v_cndmask_b32_e64 v48, 0, v71, s[18:19]
	v_cndmask_b32_e64 v18, 0, v68, s[18:19]
	v_cndmask_b32_e64 v49, 0, v69, s[18:19]
	v_cvt_pk_bf16_f32 v18, v18, v49
	v_cvt_pk_bf16_f32 v19, v19, v48
	v_add_u32_e32 v48, v217, v220
	ds_write_b64 v48, v[18:19] offset:18432
	v_cndmask_b32_e64 v19, 0, v82, s[20:21]
	v_cndmask_b32_e64 v48, 0, v83, s[20:21]
	v_cndmask_b32_e64 v18, 0, v80, s[20:21]
	v_cndmask_b32_e64 v49, 0, v81, s[20:21]
	v_cvt_pk_bf16_f32 v18, v18, v49
	v_cvt_pk_bf16_f32 v19, v19, v48
	v_add_u32_e32 v48, v217, v221
	ds_write_b64 v48, v[18:19] offset:18432
	s_waitcnt vmcnt(6)
	v_cndmask_b32_e64 v19, 0, v78, s[22:23]
	v_cndmask_b32_e64 v48, 0, v79, s[22:23]
	v_cndmask_b32_e64 v18, 0, v76, s[22:23]
	v_cndmask_b32_e64 v49, 0, v77, s[22:23]
	v_cvt_pk_bf16_f32 v18, v18, v49
	v_cvt_pk_bf16_f32 v19, v19, v48
	v_add_u32_e32 v48, v217, v222
	ds_write_b64 v48, v[18:19] offset:18432
	v_cndmask_b32_e64 v19, 0, v90, s[24:25]
	v_cndmask_b32_e64 v48, 0, v91, s[24:25]
	v_cndmask_b32_e64 v18, 0, v88, s[24:25]
	v_cndmask_b32_e64 v49, 0, v89, s[24:25]
	v_cvt_pk_bf16_f32 v18, v18, v49
	v_cvt_pk_bf16_f32 v19, v19, v48
	v_add_u32_e32 v48, v217, v223
	ds_write_b64 v48, v[18:19] offset:18432
	s_waitcnt vmcnt(5)
	v_cndmask_b32_e64 v19, 0, v86, s[26:27]
	v_cndmask_b32_e64 v48, 0, v87, s[26:27]
	v_cndmask_b32_e64 v18, 0, v84, s[26:27]
	v_cndmask_b32_e64 v49, 0, v85, s[26:27]
	v_cvt_pk_bf16_f32 v18, v18, v49
	v_cvt_pk_bf16_f32 v19, v19, v48
	v_add_u32_e32 v48, v217, v224
	ds_write_b64 v48, v[18:19] offset:18432
	v_cndmask_b32_e64 v19, 0, v98, s[28:29]
	v_cndmask_b32_e64 v48, 0, v99, s[28:29]
	v_cndmask_b32_e64 v18, 0, v96, s[28:29]
	v_cndmask_b32_e64 v49, 0, v97, s[28:29]
	v_cvt_pk_bf16_f32 v18, v18, v49
	v_cvt_pk_bf16_f32 v19, v19, v48
	v_add_u32_e32 v48, v217, v225
	ds_write_b64 v48, v[18:19] offset:18432
	s_waitcnt vmcnt(4)
	v_cndmask_b32_e64 v19, 0, v94, s[30:31]
	v_cndmask_b32_e64 v48, 0, v95, s[30:31]
	v_cndmask_b32_e64 v18, 0, v92, s[30:31]
	v_cndmask_b32_e64 v49, 0, v93, s[30:31]
	v_cvt_pk_bf16_f32 v18, v18, v49
	v_cvt_pk_bf16_f32 v19, v19, v48
	v_add_u32_e32 v48, v217, v226
	ds_write_b64 v48, v[18:19] offset:18432
	v_cndmask_b32_e64 v19, 0, v106, s[34:35]
	v_cndmask_b32_e64 v48, 0, v107, s[34:35]
	v_cndmask_b32_e64 v18, 0, v104, s[34:35]
	v_cndmask_b32_e64 v49, 0, v105, s[34:35]
	v_cvt_pk_bf16_f32 v18, v18, v49
	v_cvt_pk_bf16_f32 v19, v19, v48
	v_add_u32_e32 v48, v217, v227
	ds_write_b64 v48, v[18:19] offset:18432
	s_waitcnt vmcnt(3)
	v_cndmask_b32_e64 v19, 0, v102, s[36:37]
	v_cndmask_b32_e64 v48, 0, v103, s[36:37]
	v_cndmask_b32_e64 v18, 0, v100, s[36:37]
	v_cndmask_b32_e64 v49, 0, v101, s[36:37]
	v_cvt_pk_bf16_f32 v18, v18, v49
	v_cvt_pk_bf16_f32 v19, v19, v48
	v_add_u32_e32 v48, v217, v228
	ds_write_b64 v48, v[18:19] offset:18432
	v_cndmask_b32_e64 v19, 0, v114, s[38:39]
	v_cndmask_b32_e64 v48, 0, v115, s[38:39]
	v_cndmask_b32_e64 v18, 0, v112, s[38:39]
	v_cndmask_b32_e64 v49, 0, v113, s[38:39]
	v_cvt_pk_bf16_f32 v18, v18, v49
	v_cvt_pk_bf16_f32 v19, v19, v48
	v_add_u32_e32 v48, v217, v229
	ds_write_b64 v48, v[18:19] offset:18432
	s_waitcnt vmcnt(2)
	v_cndmask_b32_e64 v19, 0, v110, s[40:41]
	v_cndmask_b32_e64 v48, 0, v111, s[40:41]
	v_cndmask_b32_e64 v18, 0, v108, s[40:41]
	v_cndmask_b32_e64 v49, 0, v109, s[40:41]
	v_cvt_pk_bf16_f32 v18, v18, v49
	v_cvt_pk_bf16_f32 v19, v19, v48
	v_add_u32_e32 v48, v217, v230
	ds_write_b64 v48, v[18:19] offset:18432
	v_cndmask_b32_e64 v19, 0, v122, s[42:43]
	v_cndmask_b32_e64 v48, 0, v123, s[42:43]
	v_cndmask_b32_e64 v18, 0, v120, s[42:43]
	v_cndmask_b32_e64 v49, 0, v121, s[42:43]
	v_cvt_pk_bf16_f32 v18, v18, v49
	v_cvt_pk_bf16_f32 v19, v19, v48
	v_add_u32_e32 v48, v217, v231
	ds_write_b64 v48, v[18:19] offset:18432
	s_waitcnt vmcnt(1)
	v_cndmask_b32_e64 v19, 0, v118, s[44:45]
	v_cndmask_b32_e64 v48, 0, v119, s[44:45]
	v_cndmask_b32_e64 v18, 0, v116, s[44:45]
	v_cndmask_b32_e64 v49, 0, v117, s[44:45]
	v_cvt_pk_bf16_f32 v18, v18, v49
	v_cvt_pk_bf16_f32 v19, v19, v48
	v_add_u32_e32 v48, v217, v232
	ds_write_b64 v48, v[18:19] offset:18432
	s_waitcnt vmcnt(0)
	v_cndmask_b32_e64 v19, 0, v126, s[46:47]
	v_cndmask_b32_e64 v48, 0, v127, s[46:47]
	v_cndmask_b32_e64 v18, 0, v124, s[46:47]
	v_cndmask_b32_e64 v49, 0, v125, s[46:47]
	v_cvt_pk_bf16_f32 v18, v18, v49
	v_cvt_pk_bf16_f32 v19, v19, v48
	v_add_u32_e32 v48, v217, v233
	ds_write_b64 v48, v[18:19] offset:18432
	s_waitcnt lgkmcnt(0)
	v_add_u32_e32 v18, v234, v183
	ds_read_b64_tr_b16 v[50:51], v18 offset:20736
	ds_read_b64_tr_b16 v[48:49], v18 offset:18432
	ds_read_b64_tr_b16 v[52:53], v18 offset:18464
	ds_read_b64_tr_b16 v[60:61], v18 offset:23040
	ds_read_b64_tr_b16 v[62:63], v18 offset:25344
	ds_read_b64_tr_b16 v[54:55], v18 offset:20768
	ds_read_b64_tr_b16 v[64:65], v18 offset:23072
	ds_read_b64_tr_b16 v[66:67], v18 offset:25376
	ds_read_b64_tr_b16 v[68:69], v18 offset:18496
	ds_read_b64_tr_b16 v[70:71], v18 offset:20800
	ds_read_b64_tr_b16 v[72:73], v18 offset:23104
	ds_read_b64_tr_b16 v[74:75], v18 offset:25408
	ds_read_b64_tr_b16 v[76:77], v18 offset:18528
	ds_read_b64_tr_b16 v[78:79], v18 offset:20832
	ds_read_b64_tr_b16 v[80:81], v18 offset:23136
	ds_read_b64_tr_b16 v[82:83], v18 offset:25440
	s_waitcnt lgkmcnt(14)
	v_mfma_f32_16x16x32_bf16 v[44:47], v[48:51], v[56:59], v[44:47]
	s_waitcnt lgkmcnt(0)
	v_mov_b32_e32 v169, v139
	s_waitcnt lgkmcnt(10)
	v_mfma_f32_16x16x32_bf16 v[8:11], v[52:55], v[56:59], v[8:11]
	s_waitcnt lgkmcnt(6)
	v_mfma_f32_16x16x32_bf16 v[4:7], v[68:71], v[56:59], v[4:7]
	s_waitcnt lgkmcnt(2)
	v_mfma_f32_16x16x32_bf16 v[0:3], v[76:79], v[56:59], v[0:3]
	v_mfma_f32_16x16x32_bf16 v[44:47], v[60:63], v[12:15], v[44:47]
	v_mfma_f32_16x16x32_bf16 v[48:51], v[64:67], v[12:15], v[8:11]
	v_mfma_f32_16x16x32_bf16 v[52:55], v[72:75], v[12:15], v[4:7]
	s_waitcnt lgkmcnt(0)
	v_mfma_f32_16x16x32_bf16 v[56:59], v[80:83], v[12:15], v[0:3]
